# GEMM-phase rstd-table prologue: unit loop unrolled for grid 256, all SSQ loads in flight before one wait (generic loop kept as fallback)
# speedup vs baseline: 1.0513x; 1.0027x over previous
; #define LAS __attribute__((address_space(3)))
;     __device__ __forceinline__ bool next(int i, Unit& u) const {
;         const long L = (long)i * G + c; if (L >= nwg) return false;
;         int wgid = (int)L; { const int q = nwg / NXCD, r = nwg % NXCD, xcd = wgid % NXCD, off = wgid / NXCD; wgid = (xcd < r ? xcd * (q + 1) : r * (q + 1) + (xcd - r) * q) + off; }
;         const int nig = WGM * nN, gid = wgid / nig, fm = gid * WGM, gsz = (nM - fm) < WGM ? (nM - fm) : WGM;
;         u.pm = fm + ((wgid % nig) % gsz); u.pn = (wgid % nig) / gsz; u.idx = i; return true;
; __global__ void __launch_bounds__(512, 2) hybrid_fwd(Args args) {
;     ...
;         pg8::Gemm g{XB, WinE, 1024, 1024, 1024, 0, 128, 8}; pg8::StaticOrder S; S.init(128, 8, G, blk);
;         LAS float* rst = (LAS float*)(lds + 139264);
;         { pg8::Unit pu; for (int i = 0; S.next(i, pu); ++i) if (tid < 256) rst[i * 256 + tid] = row_rstd(SSQ, pu.pm * 256 + tid);
;           if (tid >= 256 && tid < 384) rst[4096 + tid - 256] = (tid < 320) ? sb_q_gain[tid - 256] : sb_k_gain[tid - 320];
;           __syncthreads(); }
.LBB0_183:
	s_cmp_lt_i32 s82, 2
	s_cselect_b64 s[8:9], -1, 0
	s_and_b64 s[10:11], s[8:9], s[6:7]
	s_andn2_b64 vcc, exec, s[10:11]
	s_cbranch_vccnz .LBB0_295
	v_mov_b32_e32 v0, v220
	s_waitcnt lgkmcnt(0)
	s_load_dword s42, s[0:1], 0xb0
	s_ashr_i32 s3, s2, 31
	s_movk_i32 s6, 0x100
	v_lshl_add_u32 v1, v0, 2, 0
	v_cmp_gt_i32_e64 s[6:7], s6, v0
	s_waitcnt lgkmcnt(0)
	s_ashr_i32 s43, s42, 31
	s_add_u32 s8, s80, 0x3400000
	s_addc_u32 s9, s81, 0
	v_add_u32_e32 v1, 0x22000, v1
	v_mov_b64_e32 v[2:3], 0x400
	v_mov_b64_e32 v[4:5], 0x3ff
	v_mov_b32_e32 v6, 0x358637bd
	s_mov_b32 s16, 0x800000
	s_mov_b64 s[12:13], s[2:3]
	s_cmp_lg_u32 s42, 0x100
	s_cbranch_scc1 .Lrs0_slow
	s_ashr_i32 s14, s12, 31
	s_lshr_b32 s14, s14, 29
	s_add_i32 s17, s12, s14
	s_and_b32 s14, s17, -8
	s_sub_i32 s18, s12, s14
	s_cmp_gt_i32 s18, -1
	s_mov_b64 s[14:15], -1
	s_cbranch_scc0 .Lrs0_0_191
	s_lshl_b32 s19, s18, 7
	s_mov_b64 s[14:15], 0

;     __device__ __forceinline__ bool next(int i, Unit& u) const {
;         const long L = (long)i * G + c; if (L >= nwg) return false;
;         int wgid = (int)L; { const int q = nwg / NXCD, r = nwg % NXCD, xcd = wgid % NXCD, off = wgid / NXCD; wgid = (xcd < r ? xcd * (q + 1) : r * (q + 1) + (xcd - r) * q) + off; }
;         const int nig = WGM * nN, gid = wgid / nig, fm = gid * WGM, gsz = (nM - fm) < WGM ? (nM - fm) : WGM;
;         u.pm = fm + ((wgid % nig) % gsz); u.pn = (wgid % nig) / gsz; u.idx = i; return true;
; __global__ void __launch_bounds__(512, 2) hybrid_fwd(Args args) {
;     ...
;         { pg8::Unit pu; for (int i = 0; S.next(i, pu); ++i) if (tid < 256) rst[i * 256 + tid] = row_rstd(SSQ, pu.pm * 256 + tid);
.Lrs0_0_193:
	s_ashr_i32 s14, s17, 3
	s_add_i32 s14, s19, s14
	s_ashr_i32 s15, s14, 31
	s_lshr_b32 s15, s15, 28
	s_add_i32 s15, s14, s15
	s_ashr_i32 s17, s15, 4
	s_lshl_b32 s17, s17, 1
	s_sub_i32 s18, 0x80, s17
	s_min_i32 s18, s18, 2
	s_abs_i32 s18, s18
	v_cvt_f32_u32_e32 v7, s18
	s_sub_i32 s19, 0, s18
	s_and_b32 s15, s15, -16
	s_sub_i32 s14, s14, s15
	v_rcp_iflag_f32_e32 v7, v7
	s_ashr_i32 s15, s14, 31
	s_abs_i32 s14, s14
	v_mul_f32_e32 v7, 0x4f7ffffe, v7
	v_cvt_u32_f32_e32 v7, v7
	s_nop 0
	v_readfirstlane_b32 s20, v7
	s_mul_i32 s19, s19, s20
	s_mul_hi_u32 s19, s20, s19
	s_add_i32 s20, s20, s19
	s_mul_hi_u32 s19, s14, s20
	s_mul_i32 s19, s19, s18
	s_sub_i32 s14, s14, s19
	s_sub_i32 s19, s14, s18
	s_cmp_ge_u32 s14, s18
	s_cselect_b32 s14, s19, s14
	s_sub_i32 s19, s14, s18
	s_cmp_ge_u32 s14, s18
	s_cselect_b32 s14, s19, s14
	s_xor_b32 s14, s14, s15
	s_sub_i32 s14, s14, s15
	s_add_i32 s17, s17, s14
	s_and_saveexec_b64 s[14:15], s[6:7]
	v_lshl_add_u32 v32, s17, 8, v0
	v_ashrrev_i32_e32 v33, 31, v32
	v_lshlrev_b64 v[32:33], 6, v[32:33]
	v_lshl_add_u64 v[24:25], s[8:9], 0, v[32:33]
	global_load_dwordx4 v[32:35], v[24:25], off
	global_load_dwordx4 v[36:39], v[24:25], off offset:16
	global_load_dwordx4 v[40:43], v[24:25], off offset:32
	global_load_dwordx4 v[44:47], v[24:25], off offset:48
	s_or_b64 exec, exec, s[14:15]
	s_add_u32 s12, s12, s42
	s_addc_u32 s13, s13, s43
	s_ashr_i32 s14, s12, 31
	s_lshr_b32 s14, s14, 29
	s_add_i32 s17, s12, s14
	s_and_b32 s14, s17, -8
	s_sub_i32 s18, s12, s14
	s_cmp_gt_i32 s18, -1
	s_mov_b64 s[14:15], -1
	s_cbranch_scc0 .Lrs0_1_191
	s_lshl_b32 s19, s18, 7
	s_mov_b64 s[14:15], 0

;     __device__ __forceinline__ bool next(int i, Unit& u) const {
;         const long L = (long)i * G + c; if (L >= nwg) return false;
;         int wgid = (int)L; { const int q = nwg / NXCD, r = nwg % NXCD, xcd = wgid % NXCD, off = wgid / NXCD; wgid = (xcd < r ? xcd * (q + 1) : r * (q + 1) + (xcd - r) * q) + off; }
;         const int nig = WGM * nN, gid = wgid / nig, fm = gid * WGM, gsz = (nM - fm) < WGM ? (nM - fm) : WGM;
;         u.pm = fm + ((wgid % nig) % gsz); u.pn = (wgid % nig) / gsz; u.idx = i; return true;
; __global__ void __launch_bounds__(512, 2) hybrid_fwd(Args args) {
;     ...
;         { pg8::Unit pu; for (int i = 0; S.next(i, pu); ++i) if (tid < 256) rst[i * 256 + tid] = row_rstd(SSQ, pu.pm * 256 + tid);
.Lrs0_1_193:
	s_ashr_i32 s14, s17, 3
	s_add_i32 s14, s19, s14
	s_ashr_i32 s15, s14, 31
	s_lshr_b32 s15, s15, 28
	s_add_i32 s15, s14, s15
	s_ashr_i32 s17, s15, 4
	s_lshl_b32 s17, s17, 1
	s_sub_i32 s18, 0x80, s17
	s_min_i32 s18, s18, 2
	s_abs_i32 s18, s18
	v_cvt_f32_u32_e32 v7, s18
	s_sub_i32 s19, 0, s18
	s_and_b32 s15, s15, -16
	s_sub_i32 s14, s14, s15
	v_rcp_iflag_f32_e32 v7, v7
	s_ashr_i32 s15, s14, 31
	s_abs_i32 s14, s14
	v_mul_f32_e32 v7, 0x4f7ffffe, v7
	v_cvt_u32_f32_e32 v7, v7
	s_nop 0
	v_readfirstlane_b32 s20, v7
	s_mul_i32 s19, s19, s20
	s_mul_hi_u32 s19, s20, s19
	s_add_i32 s20, s20, s19
	s_mul_hi_u32 s19, s14, s20
	s_mul_i32 s19, s19, s18
	s_sub_i32 s14, s14, s19
	s_sub_i32 s19, s14, s18
	s_cmp_ge_u32 s14, s18
	s_cselect_b32 s14, s19, s14
	s_sub_i32 s19, s14, s18
	s_cmp_ge_u32 s14, s18
	s_cselect_b32 s14, s19, s14
	s_xor_b32 s14, s14, s15
	s_sub_i32 s14, s14, s15
	s_add_i32 s17, s17, s14
	s_and_saveexec_b64 s[14:15], s[6:7]
	v_lshl_add_u32 v48, s17, 8, v0
	v_ashrrev_i32_e32 v49, 31, v48
	v_lshlrev_b64 v[48:49], 6, v[48:49]
	v_lshl_add_u64 v[24:25], s[8:9], 0, v[48:49]
	global_load_dwordx4 v[48:51], v[24:25], off
	global_load_dwordx4 v[52:55], v[24:25], off offset:16
	global_load_dwordx4 v[56:59], v[24:25], off offset:32
	global_load_dwordx4 v[60:63], v[24:25], off offset:48
	s_or_b64 exec, exec, s[14:15]
	s_add_u32 s12, s12, s42
	s_addc_u32 s13, s13, s43
	s_ashr_i32 s14, s12, 31
	s_lshr_b32 s14, s14, 29
	s_add_i32 s17, s12, s14
	s_and_b32 s14, s17, -8
	s_sub_i32 s18, s12, s14
	s_cmp_gt_i32 s18, -1
	s_mov_b64 s[14:15], -1
	s_cbranch_scc0 .Lrs0_2_191
	s_lshl_b32 s19, s18, 7
	s_mov_b64 s[14:15], 0

;     __device__ __forceinline__ bool next(int i, Unit& u) const {
;         const long L = (long)i * G + c; if (L >= nwg) return false;
;         int wgid = (int)L; { const int q = nwg / NXCD, r = nwg % NXCD, xcd = wgid % NXCD, off = wgid / NXCD; wgid = (xcd < r ? xcd * (q + 1) : r * (q + 1) + (xcd - r) * q) + off; }
;         const int nig = WGM * nN, gid = wgid / nig, fm = gid * WGM, gsz = (nM - fm) < WGM ? (nM - fm) : WGM;
;         u.pm = fm + ((wgid % nig) % gsz); u.pn = (wgid % nig) / gsz; u.idx = i; return true;
; __global__ void __launch_bounds__(512, 2) hybrid_fwd(Args args) {
;     ...
;         { pg8::Unit pu; for (int i = 0; S.next(i, pu); ++i) if (tid < 256) rst[i * 256 + tid] = row_rstd(SSQ, pu.pm * 256 + tid);
.Lrs0_2_193:
	s_ashr_i32 s14, s17, 3
	s_add_i32 s14, s19, s14
	s_ashr_i32 s15, s14, 31
	s_lshr_b32 s15, s15, 28
	s_add_i32 s15, s14, s15
	s_ashr_i32 s17, s15, 4
	s_lshl_b32 s17, s17, 1
	s_sub_i32 s18, 0x80, s17
	s_min_i32 s18, s18, 2
	s_abs_i32 s18, s18
	v_cvt_f32_u32_e32 v7, s18
	s_sub_i32 s19, 0, s18
	s_and_b32 s15, s15, -16
	s_sub_i32 s14, s14, s15
	v_rcp_iflag_f32_e32 v7, v7
	s_ashr_i32 s15, s14, 31
	s_abs_i32 s14, s14
	v_mul_f32_e32 v7, 0x4f7ffffe, v7
	v_cvt_u32_f32_e32 v7, v7
	s_nop 0
	v_readfirstlane_b32 s20, v7
	s_mul_i32 s19, s19, s20
	s_mul_hi_u32 s19, s20, s19
	s_add_i32 s20, s20, s19
	s_mul_hi_u32 s19, s14, s20
	s_mul_i32 s19, s19, s18
	s_sub_i32 s14, s14, s19
	s_sub_i32 s19, s14, s18
	s_cmp_ge_u32 s14, s18
	s_cselect_b32 s14, s19, s14
	s_sub_i32 s19, s14, s18
	s_cmp_ge_u32 s14, s18
	s_cselect_b32 s14, s19, s14
	s_xor_b32 s14, s14, s15
	s_sub_i32 s14, s14, s15
	s_add_i32 s17, s17, s14
	s_and_saveexec_b64 s[14:15], s[6:7]
	v_lshl_add_u32 v64, s17, 8, v0
	v_ashrrev_i32_e32 v65, 31, v64
	v_lshlrev_b64 v[64:65], 6, v[64:65]
	v_lshl_add_u64 v[24:25], s[8:9], 0, v[64:65]
	global_load_dwordx4 v[64:67], v[24:25], off
	global_load_dwordx4 v[68:71], v[24:25], off offset:16
	global_load_dwordx4 v[72:75], v[24:25], off offset:32
	global_load_dwordx4 v[76:79], v[24:25], off offset:48
	s_or_b64 exec, exec, s[14:15]
	s_add_u32 s12, s12, s42
	s_addc_u32 s13, s13, s43
	s_ashr_i32 s14, s12, 31
	s_lshr_b32 s14, s14, 29
	s_add_i32 s17, s12, s14
	s_and_b32 s14, s17, -8
	s_sub_i32 s18, s12, s14
	s_cmp_gt_i32 s18, -1
	s_mov_b64 s[14:15], -1
	s_cbranch_scc0 .Lrs0_3_191
	s_lshl_b32 s19, s18, 7
	s_mov_b64 s[14:15], 0

; __device__ __forceinline__ float row_rstd(const float* ssq, int row) {
;     const f32x4* p = (const f32x4*)(ssq + (size_t)row * 16);
;     const f32x4 a = p[0], b = p[1], c = p[2], d = p[3];
;     const float s = ((a[0] + a[1]) + (a[2] + a[3])) + ((b[0] + b[1]) + (b[2] + b[3])) + ((c[0] + c[1]) + (c[2] + c[3])) + ((d[0] + d[1]) + (d[2] + d[3]));
;     return rsqrtf(s * (1.0f / 1024.0f) + EPS);
; }
; __global__ void __launch_bounds__(512, 2) hybrid_fwd(Args args) {
;     ...
;         { pg8::Unit pu; for (int i = 0; S.next(i, pu); ++i) if (tid < 256) rst[i * 256 + tid] = row_rstd(SSQ, pu.pm * 256 + tid);
.Lrs0_3_193:
	s_ashr_i32 s14, s17, 3
	s_add_i32 s14, s19, s14
	s_ashr_i32 s15, s14, 31
	s_lshr_b32 s15, s15, 28
	s_add_i32 s15, s14, s15
	s_ashr_i32 s17, s15, 4
	s_lshl_b32 s17, s17, 1
	s_sub_i32 s18, 0x80, s17
	s_min_i32 s18, s18, 2
	s_abs_i32 s18, s18
	v_cvt_f32_u32_e32 v7, s18
	s_sub_i32 s19, 0, s18
	s_and_b32 s15, s15, -16
	s_sub_i32 s14, s14, s15
	v_rcp_iflag_f32_e32 v7, v7
	s_ashr_i32 s15, s14, 31
	s_abs_i32 s14, s14
	v_mul_f32_e32 v7, 0x4f7ffffe, v7
	v_cvt_u32_f32_e32 v7, v7
	s_nop 0
	v_readfirstlane_b32 s20, v7
	s_mul_i32 s19, s19, s20
	s_mul_hi_u32 s19, s20, s19
	s_add_i32 s20, s20, s19
	s_mul_hi_u32 s19, s14, s20
	s_mul_i32 s19, s19, s18
	s_sub_i32 s14, s14, s19
	s_sub_i32 s19, s14, s18
	s_cmp_ge_u32 s14, s18
	s_cselect_b32 s14, s19, s14
	s_sub_i32 s19, s14, s18
	s_cmp_ge_u32 s14, s18
	s_cselect_b32 s14, s19, s14
	s_xor_b32 s14, s14, s15
	s_sub_i32 s14, s14, s15
	s_add_i32 s17, s17, s14
	s_and_saveexec_b64 s[14:15], s[6:7]
	v_lshl_add_u32 v80, s17, 8, v0
	v_ashrrev_i32_e32 v81, 31, v80
	v_lshlrev_b64 v[80:81], 6, v[80:81]
	v_lshl_add_u64 v[24:25], s[8:9], 0, v[80:81]
	global_load_dwordx4 v[80:83], v[24:25], off
	global_load_dwordx4 v[84:87], v[24:25], off offset:16
	global_load_dwordx4 v[88:91], v[24:25], off offset:32
	global_load_dwordx4 v[92:95], v[24:25], off offset:48
	s_or_b64 exec, exec, s[14:15]
	s_and_saveexec_b64 s[14:15], s[6:7]
	s_waitcnt vmcnt(0)
	v_mov_b32_e32 v24, v33
	v_mov_b32_e32 v25, v34
	v_mov_b32_e32 v33, v35
	v_mov_b32_e32 v34, v37
	v_mov_b32_e32 v35, v38
	v_mov_b32_e32 v37, v39
	v_pk_add_f32 v[32:33], v[24:25], v[32:33]
	v_pk_add_f32 v[34:35], v[34:35], v[36:37]
	v_pk_add_f32 v[32:33], v[32:33], v[32:33] op_sel:[0,1] op_sel_hi:[1,0]
	v_pk_add_f32 v[34:35], v[34:35], v[34:35] op_sel:[0,1] op_sel_hi:[1,0]
	v_add_f32_e32 v38, v40, v41
	v_add_f32_e32 v40, v42, v43
	v_mov_b32_e32 v39, v46
	v_mov_b32_e32 v41, v47
	v_mov_b32_e32 v33, v44
	v_mov_b32_e32 v35, v45
	v_pk_add_f32 v[36:37], v[38:39], v[40:41]
	v_pk_add_f32 v[32:33], v[32:33], v[34:35]
	s_nop 0
	v_pk_add_f32 v[32:33], v[32:33], v[36:37]
	s_nop 0
	v_add_f32_e32 v7, v32, v33
	v_fmamk_f32 v7, v7, 0x3a800000, v6
	v_mul_f32_e32 v32, 0x4b800000, v7
	v_cmp_gt_f32_e32 vcc, s16, v7
	s_nop 1
	v_cndmask_b32_e32 v7, v7, v32, vcc
	v_rsq_f32_e32 v7, v7
	s_nop 0
	v_mul_f32_e32 v32, 0x45800000, v7
	v_cndmask_b32_e32 v7, v7, v32, vcc
	ds_write_b32 v1, v7
	v_mov_b32_e32 v24, v49
	v_mov_b32_e32 v25, v50
	v_mov_b32_e32 v49, v51
	v_mov_b32_e32 v50, v53
	v_mov_b32_e32 v51, v54
	v_mov_b32_e32 v53, v55
	v_pk_add_f32 v[48:49], v[24:25], v[48:49]
	v_pk_add_f32 v[50:51], v[50:51], v[52:53]
	v_pk_add_f32 v[48:49], v[48:49], v[48:49] op_sel:[0,1] op_sel_hi:[1,0]
	v_pk_add_f32 v[50:51], v[50:51], v[50:51] op_sel:[0,1] op_sel_hi:[1,0]
	v_add_f32_e32 v54, v56, v57
	v_add_f32_e32 v56, v58, v59
	v_mov_b32_e32 v55, v62
	v_mov_b32_e32 v57, v63
	v_mov_b32_e32 v49, v60
	v_mov_b32_e32 v51, v61
	v_pk_add_f32 v[52:53], v[54:55], v[56:57]
	v_pk_add_f32 v[48:49], v[48:49], v[50:51]
	s_nop 0
	v_pk_add_f32 v[48:49], v[48:49], v[52:53]
	s_nop 0
	v_add_f32_e32 v7, v48, v49
	v_fmamk_f32 v7, v7, 0x3a800000, v6
	v_mul_f32_e32 v48, 0x4b800000, v7
	v_cmp_gt_f32_e32 vcc, s16, v7
	s_nop 1
	v_cndmask_b32_e32 v7, v7, v48, vcc
	v_rsq_f32_e32 v7, v7
	s_nop 0
	v_mul_f32_e32 v48, 0x45800000, v7
	v_cndmask_b32_e32 v7, v7, v48, vcc
	ds_write_b32 v1, v7 offset:1024
	v_mov_b32_e32 v24, v65
	v_mov_b32_e32 v25, v66
	v_mov_b32_e32 v65, v67
	v_mov_b32_e32 v66, v69
	v_mov_b32_e32 v67, v70
	v_mov_b32_e32 v69, v71
	v_pk_add_f32 v[64:65], v[24:25], v[64:65]
	v_pk_add_f32 v[66:67], v[66:67], v[68:69]
	v_pk_add_f32 v[64:65], v[64:65], v[64:65] op_sel:[0,1] op_sel_hi:[1,0]
	v_pk_add_f32 v[66:67], v[66:67], v[66:67] op_sel:[0,1] op_sel_hi:[1,0]
	v_add_f32_e32 v70, v72, v73
	v_add_f32_e32 v72, v74, v75
	v_mov_b32_e32 v71, v78
	v_mov_b32_e32 v73, v79
	v_mov_b32_e32 v65, v76
	v_mov_b32_e32 v67, v77
	v_pk_add_f32 v[68:69], v[70:71], v[72:73]
	v_pk_add_f32 v[64:65], v[64:65], v[66:67]
	s_nop 0
	v_pk_add_f32 v[64:65], v[64:65], v[68:69]
	s_nop 0
	v_add_f32_e32 v7, v64, v65
	v_fmamk_f32 v7, v7, 0x3a800000, v6
	v_mul_f32_e32 v64, 0x4b800000, v7
	v_cmp_gt_f32_e32 vcc, s16, v7
	s_nop 1
	v_cndmask_b32_e32 v7, v7, v64, vcc
	v_rsq_f32_e32 v7, v7
	s_nop 0
	v_mul_f32_e32 v64, 0x45800000, v7
	v_cndmask_b32_e32 v7, v7, v64, vcc
	ds_write_b32 v1, v7 offset:2048
	v_mov_b32_e32 v24, v81
	v_mov_b32_e32 v25, v82
	v_mov_b32_e32 v81, v83
	v_mov_b32_e32 v82, v85
	v_mov_b32_e32 v83, v86
	v_mov_b32_e32 v85, v87
	v_pk_add_f32 v[80:81], v[24:25], v[80:81]
	v_pk_add_f32 v[82:83], v[82:83], v[84:85]
	v_pk_add_f32 v[80:81], v[80:81], v[80:81] op_sel:[0,1] op_sel_hi:[1,0]
	v_pk_add_f32 v[82:83], v[82:83], v[82:83] op_sel:[0,1] op_sel_hi:[1,0]
	v_add_f32_e32 v86, v88, v89
	v_add_f32_e32 v88, v90, v91
	v_mov_b32_e32 v87, v94
	v_mov_b32_e32 v89, v95
	v_mov_b32_e32 v81, v92
	v_mov_b32_e32 v83, v93
	v_pk_add_f32 v[84:85], v[86:87], v[88:89]
	v_pk_add_f32 v[80:81], v[80:81], v[82:83]
	s_nop 0
	v_pk_add_f32 v[80:81], v[80:81], v[84:85]
	s_nop 0
	v_add_f32_e32 v7, v80, v81
	v_fmamk_f32 v7, v7, 0x3a800000, v6
	v_mul_f32_e32 v80, 0x4b800000, v7
	v_cmp_gt_f32_e32 vcc, s16, v7
	s_nop 1
	v_cndmask_b32_e32 v7, v7, v80, vcc
	v_rsq_f32_e32 v7, v7
	s_nop 0
	v_mul_f32_e32 v80, 0x45800000, v7
	v_cndmask_b32_e32 v7, v7, v80, vcc
	ds_write_b32 v1, v7 offset:3072
	s_or_b64 exec, exec, s[14:15]
	s_branch .LBB0_196
.Lrs0_slow:
	s_branch .LBB0_187

; #define LAS __attribute__((address_space(3)))
;     __device__ __forceinline__ bool next(int i, Unit& u) const {
;         const long L = (long)i * G + c; if (L >= nwg) return false;
;         int wgid = (int)L; { const int q = nwg / NXCD, r = nwg % NXCD, xcd = wgid % NXCD, off = wgid / NXCD; wgid = (xcd < r ? xcd * (q + 1) : r * (q + 1) + (xcd - r) * q) + off; }
;         const int nig = WGM * nN, gid = wgid / nig, fm = gid * WGM, gsz = (nM - fm) < WGM ? (nM - fm) : WGM;
;         u.pm = fm + ((wgid % nig) % gsz); u.pn = (wgid % nig) / gsz; u.idx = i; return true;
; __global__ void __launch_bounds__(512, 2) hybrid_fwd(Args args) {
;     ...
;         pg8::Gemm g{XB, Wup, 1024, 1024, 1024, 0, 128, 22}; pg8::StaticOrder S; S.init(128, 22, G, blk);
;         LAS float* rst = (LAS float*)(lds + 139264);
;         { pg8::Unit pu; for (int i = 0; S.next(i, pu); ++i) if (tid < 256) rst[i * 256 + tid] = row_rstd(SSQ + SSQ_STRIDE, pu.pm * 256 + tid);
;           __syncthreads(); }
.LBB0_576:
	s_cmp_lt_i32 s82, 6
	s_cselect_b64 s[8:9], -1, 0
	s_and_b64 s[18:19], s[8:9], s[6:7]
	s_andn2_b64 vcc, exec, s[18:19]
	s_cbranch_vccnz .LBB0_636
	v_mov_b32_e32 v4, v220
	s_load_dword s52, s[0:1], 0xb0
	s_waitcnt lgkmcnt(0)
	s_ashr_i32 s3, s2, 31
	s_movk_i32 s6, 0x100
	v_lshl_add_u32 v0, v4, 2, 0
	v_cmp_gt_i32_e64 s[6:7], s6, v4
	s_ashr_i32 s53, s52, 31
	s_add_u32 s8, s80, 0x3600000
	s_addc_u32 s9, s81, 0
	v_add_u32_e32 v5, 0x22000, v0
	v_mov_b64_e32 v[0:1], 0xb00
	v_mov_b64_e32 v[2:3], 0xaff
	s_movk_i32 s14, 0x161
	v_mov_b32_e32 v6, 0x358637bd
	s_mov_b32 s15, 0x800000
	s_mov_b64 s[10:11], s[2:3]
	s_cmp_lg_u32 s52, 0x100
	s_cbranch_scc1 .Lrs1_slow
	s_ashr_i32 s12, s10, 31
	s_lshr_b32 s12, s12, 29
	s_add_i32 s12, s10, s12
	s_ashr_i32 s13, s12, 3
	s_and_b32 s12, s12, -8
	s_sub_i32 s12, s10, s12
	s_cmp_lt_i32 s12, 0
	s_cselect_b32 s16, s14, 0x160
	s_mul_i32 s12, s12, s16
	s_add_i32 s12, s12, s13
	s_mul_hi_i32 s13, s12, 0x2e8ba2e9
	s_lshr_b32 s16, s13, 31
	s_ashr_i32 s13, s13, 3
	s_add_i32 s13, s13, s16
	s_lshl_b32 s16, s13, 1
	s_sub_i32 s17, 0x80, s16
	s_min_i32 s17, s17, 2
	s_abs_i32 s17, s17
	v_cvt_f32_u32_e32 v7, s17
	s_sub_i32 s20, 0, s17
	s_mul_i32 s13, s13, 44
	s_sub_i32 s12, s12, s13
	v_rcp_iflag_f32_e32 v7, v7
	s_ashr_i32 s13, s12, 31
	s_abs_i32 s12, s12
	v_mul_f32_e32 v7, 0x4f7ffffe, v7
	v_cvt_u32_f32_e32 v7, v7
	s_nop 0
	v_readfirstlane_b32 s21, v7
	s_mul_i32 s20, s20, s21
	s_mul_hi_u32 s20, s21, s20
	s_add_i32 s21, s21, s20
	s_mul_hi_u32 s20, s12, s21
	s_mul_i32 s20, s20, s17
	s_sub_i32 s12, s12, s20
	s_sub_i32 s20, s12, s17
	s_cmp_ge_u32 s12, s17
	s_cselect_b32 s12, s20, s12
	s_sub_i32 s20, s12, s17
	s_cmp_ge_u32 s12, s17
	s_cselect_b32 s12, s20, s12
	s_xor_b32 s12, s12, s13
	s_sub_i32 s12, s12, s13
	s_add_i32 s16, s16, s12
	s_and_saveexec_b64 s[12:13], s[6:7]
	v_lshl_add_u32 v32, s16, 8, v4
	v_ashrrev_i32_e32 v33, 31, v32
	v_lshlrev_b64 v[32:33], 6, v[32:33]
	v_lshl_add_u64 v[24:25], s[8:9], 0, v[32:33]
	global_load_dwordx4 v[32:35], v[24:25], off
	global_load_dwordx4 v[36:39], v[24:25], off offset:16
	global_load_dwordx4 v[40:43], v[24:25], off offset:32
	global_load_dwordx4 v[44:47], v[24:25], off offset:48
	s_or_b64 exec, exec, s[12:13]
	s_add_u32 s10, s10, s52
	s_addc_u32 s11, s11, s53
	s_ashr_i32 s12, s10, 31
	s_lshr_b32 s12, s12, 29
	s_add_i32 s12, s10, s12
	s_ashr_i32 s13, s12, 3
	s_and_b32 s12, s12, -8
	s_sub_i32 s12, s10, s12
	s_cmp_lt_i32 s12, 0
	s_cselect_b32 s16, s14, 0x160
	s_mul_i32 s12, s12, s16
	s_add_i32 s12, s12, s13
	s_mul_hi_i32 s13, s12, 0x2e8ba2e9
	s_lshr_b32 s16, s13, 31
	s_ashr_i32 s13, s13, 3
	s_add_i32 s13, s13, s16
	s_lshl_b32 s16, s13, 1
	s_sub_i32 s17, 0x80, s16
	s_min_i32 s17, s17, 2
	s_abs_i32 s17, s17
	v_cvt_f32_u32_e32 v7, s17
	s_sub_i32 s20, 0, s17
	s_mul_i32 s13, s13, 44
	s_sub_i32 s12, s12, s13
	v_rcp_iflag_f32_e32 v7, v7
	s_ashr_i32 s13, s12, 31
	s_abs_i32 s12, s12
	v_mul_f32_e32 v7, 0x4f7ffffe, v7
	v_cvt_u32_f32_e32 v7, v7
	s_nop 0
	v_readfirstlane_b32 s21, v7
	s_mul_i32 s20, s20, s21
	s_mul_hi_u32 s20, s21, s20
	s_add_i32 s21, s21, s20
	s_mul_hi_u32 s20, s12, s21
	s_mul_i32 s20, s20, s17
	s_sub_i32 s12, s12, s20
	s_sub_i32 s20, s12, s17
	s_cmp_ge_u32 s12, s17
	s_cselect_b32 s12, s20, s12
	s_sub_i32 s20, s12, s17
	s_cmp_ge_u32 s12, s17
	s_cselect_b32 s12, s20, s12
	s_xor_b32 s12, s12, s13
	s_sub_i32 s12, s12, s13
	s_add_i32 s16, s16, s12
	s_and_saveexec_b64 s[12:13], s[6:7]
	v_lshl_add_u32 v48, s16, 8, v4
	v_ashrrev_i32_e32 v49, 31, v48
	v_lshlrev_b64 v[48:49], 6, v[48:49]
	v_lshl_add_u64 v[24:25], s[8:9], 0, v[48:49]
	global_load_dwordx4 v[48:51], v[24:25], off
	global_load_dwordx4 v[52:55], v[24:25], off offset:16
	global_load_dwordx4 v[56:59], v[24:25], off offset:32
	global_load_dwordx4 v[60:63], v[24:25], off offset:48
	s_or_b64 exec, exec, s[12:13]
	s_add_u32 s10, s10, s52
	s_addc_u32 s11, s11, s53
	s_ashr_i32 s12, s10, 31
	s_lshr_b32 s12, s12, 29
	s_add_i32 s12, s10, s12
	s_ashr_i32 s13, s12, 3
	s_and_b32 s12, s12, -8
	s_sub_i32 s12, s10, s12
	s_cmp_lt_i32 s12, 0
	s_cselect_b32 s16, s14, 0x160
	s_mul_i32 s12, s12, s16
	s_add_i32 s12, s12, s13
	s_mul_hi_i32 s13, s12, 0x2e8ba2e9
	s_lshr_b32 s16, s13, 31
	s_ashr_i32 s13, s13, 3
	s_add_i32 s13, s13, s16
	s_lshl_b32 s16, s13, 1
	s_sub_i32 s17, 0x80, s16
	s_min_i32 s17, s17, 2
	s_abs_i32 s17, s17
	v_cvt_f32_u32_e32 v7, s17
	s_sub_i32 s20, 0, s17
	s_mul_i32 s13, s13, 44
	s_sub_i32 s12, s12, s13
	v_rcp_iflag_f32_e32 v7, v7
	s_ashr_i32 s13, s12, 31
	s_abs_i32 s12, s12
	v_mul_f32_e32 v7, 0x4f7ffffe, v7
	v_cvt_u32_f32_e32 v7, v7
	s_nop 0
	v_readfirstlane_b32 s21, v7
	s_mul_i32 s20, s20, s21
	s_mul_hi_u32 s20, s21, s20
	s_add_i32 s21, s21, s20
	s_mul_hi_u32 s20, s12, s21
	s_mul_i32 s20, s20, s17
	s_sub_i32 s12, s12, s20
	s_sub_i32 s20, s12, s17
	s_cmp_ge_u32 s12, s17
	s_cselect_b32 s12, s20, s12
	s_sub_i32 s20, s12, s17
	s_cmp_ge_u32 s12, s17
	s_cselect_b32 s12, s20, s12
	s_xor_b32 s12, s12, s13
	s_sub_i32 s12, s12, s13
	s_add_i32 s16, s16, s12
	s_and_saveexec_b64 s[12:13], s[6:7]
	v_lshl_add_u32 v64, s16, 8, v4
	v_ashrrev_i32_e32 v65, 31, v64
	v_lshlrev_b64 v[64:65], 6, v[64:65]
	v_lshl_add_u64 v[24:25], s[8:9], 0, v[64:65]
	global_load_dwordx4 v[64:67], v[24:25], off
	global_load_dwordx4 v[68:71], v[24:25], off offset:16
	global_load_dwordx4 v[72:75], v[24:25], off offset:32
	global_load_dwordx4 v[76:79], v[24:25], off offset:48
	s_or_b64 exec, exec, s[12:13]
	s_add_u32 s10, s10, s52
	s_addc_u32 s11, s11, s53
	s_ashr_i32 s12, s10, 31
	s_lshr_b32 s12, s12, 29
	s_add_i32 s12, s10, s12
	s_ashr_i32 s13, s12, 3
	s_and_b32 s12, s12, -8
	s_sub_i32 s12, s10, s12
	s_cmp_lt_i32 s12, 0
	s_cselect_b32 s16, s14, 0x160
	s_mul_i32 s12, s12, s16
; #define LAS __attribute__((address_space(3)))
;     __device__ __forceinline__ bool next(int i, Unit& u) const {
;         const long L = (long)i * G + c; if (L >= nwg) return false;
;         int wgid = (int)L; { const int q = nwg / NXCD, r = nwg % NXCD, xcd = wgid % NXCD, off = wgid / NXCD; wgid = (xcd < r ? xcd * (q + 1) : r * (q + 1) + (xcd - r) * q) + off; }
;         const int nig = WGM * nN, gid = wgid / nig, fm = gid * WGM, gsz = (nM - fm) < WGM ? (nM - fm) : WGM;
;         u.pm = fm + ((wgid % nig) % gsz); u.pn = (wgid % nig) / gsz; u.idx = i; return true;
; __global__ void __launch_bounds__(512, 2) hybrid_fwd(Args args) {
;     ...
;         pg8::Gemm g{XB, Wup, 1024, 1024, 1024, 0, 128, 22}; pg8::StaticOrder S; S.init(128, 22, G, blk);
;         LAS float* rst = (LAS float*)(lds + 139264);
;         { pg8::Unit pu; for (int i = 0; S.next(i, pu); ++i) if (tid < 256) rst[i * 256 + tid] = row_rstd(SSQ + SSQ_STRIDE, pu.pm * 256 + tid);
;           __syncthreads(); }
	s_add_i32 s12, s12, s13
	s_mul_hi_i32 s13, s12, 0x2e8ba2e9
	s_lshr_b32 s16, s13, 31
	s_ashr_i32 s13, s13, 3
	s_add_i32 s13, s13, s16
	s_lshl_b32 s16, s13, 1
	s_sub_i32 s17, 0x80, s16
	s_min_i32 s17, s17, 2
	s_abs_i32 s17, s17
	v_cvt_f32_u32_e32 v7, s17
	s_sub_i32 s20, 0, s17
	s_mul_i32 s13, s13, 44
	s_sub_i32 s12, s12, s13
	v_rcp_iflag_f32_e32 v7, v7
	s_ashr_i32 s13, s12, 31
	s_abs_i32 s12, s12
	v_mul_f32_e32 v7, 0x4f7ffffe, v7
	v_cvt_u32_f32_e32 v7, v7
	s_nop 0
	v_readfirstlane_b32 s21, v7
	s_mul_i32 s20, s20, s21
	s_mul_hi_u32 s20, s21, s20
	s_add_i32 s21, s21, s20
	s_mul_hi_u32 s20, s12, s21
	s_mul_i32 s20, s20, s17
	s_sub_i32 s12, s12, s20
	s_sub_i32 s20, s12, s17
	s_cmp_ge_u32 s12, s17
	s_cselect_b32 s12, s20, s12
	s_sub_i32 s20, s12, s17
	s_cmp_ge_u32 s12, s17
	s_cselect_b32 s12, s20, s12
	s_xor_b32 s12, s12, s13
	s_sub_i32 s12, s12, s13
	s_add_i32 s16, s16, s12
	s_and_saveexec_b64 s[12:13], s[6:7]
	v_lshl_add_u32 v80, s16, 8, v4
	v_ashrrev_i32_e32 v81, 31, v80
	v_lshlrev_b64 v[80:81], 6, v[80:81]
	v_lshl_add_u64 v[24:25], s[8:9], 0, v[80:81]
	global_load_dwordx4 v[80:83], v[24:25], off
	global_load_dwordx4 v[84:87], v[24:25], off offset:16
	global_load_dwordx4 v[88:91], v[24:25], off offset:32
	global_load_dwordx4 v[92:95], v[24:25], off offset:48
	s_or_b64 exec, exec, s[12:13]
	s_add_u32 s10, s10, s52
	s_addc_u32 s11, s11, s53
	s_ashr_i32 s12, s10, 31
	s_lshr_b32 s12, s12, 29
	s_add_i32 s12, s10, s12
	s_ashr_i32 s13, s12, 3
	s_and_b32 s12, s12, -8
	s_sub_i32 s12, s10, s12
	s_cmp_lt_i32 s12, 0
	s_cselect_b32 s16, s14, 0x160
	s_mul_i32 s12, s12, s16
	s_add_i32 s12, s12, s13
	s_mul_hi_i32 s13, s12, 0x2e8ba2e9
	s_lshr_b32 s16, s13, 31
	s_ashr_i32 s13, s13, 3
	s_add_i32 s13, s13, s16
	s_lshl_b32 s16, s13, 1
	s_sub_i32 s17, 0x80, s16
	s_min_i32 s17, s17, 2
	s_abs_i32 s17, s17
	v_cvt_f32_u32_e32 v7, s17
	s_sub_i32 s20, 0, s17
	s_mul_i32 s13, s13, 44
	s_sub_i32 s12, s12, s13
	v_rcp_iflag_f32_e32 v7, v7
	s_ashr_i32 s13, s12, 31
	s_abs_i32 s12, s12
	v_mul_f32_e32 v7, 0x4f7ffffe, v7
	v_cvt_u32_f32_e32 v7, v7
	s_nop 0
	v_readfirstlane_b32 s21, v7
	s_mul_i32 s20, s20, s21
	s_mul_hi_u32 s20, s21, s20
	s_add_i32 s21, s21, s20
	s_mul_hi_u32 s20, s12, s21
	s_mul_i32 s20, s20, s17
	s_sub_i32 s12, s12, s20
	s_sub_i32 s20, s12, s17
	s_cmp_ge_u32 s12, s17
	s_cselect_b32 s12, s20, s12
	s_sub_i32 s20, s12, s17
	s_cmp_ge_u32 s12, s17
	s_cselect_b32 s12, s20, s12
	s_xor_b32 s12, s12, s13
	s_sub_i32 s12, s12, s13
	s_add_i32 s16, s16, s12
	s_and_saveexec_b64 s[12:13], s[6:7]
	v_lshl_add_u32 v96, s16, 8, v4
	v_ashrrev_i32_e32 v97, 31, v96
	v_lshlrev_b64 v[96:97], 6, v[96:97]
	v_lshl_add_u64 v[24:25], s[8:9], 0, v[96:97]
	global_load_dwordx4 v[96:99], v[24:25], off
	global_load_dwordx4 v[100:103], v[24:25], off offset:16
	global_load_dwordx4 v[104:107], v[24:25], off offset:32
	global_load_dwordx4 v[108:111], v[24:25], off offset:48
	s_or_b64 exec, exec, s[12:13]
	s_add_u32 s10, s10, s52
	s_addc_u32 s11, s11, s53
	s_ashr_i32 s12, s10, 31
	s_lshr_b32 s12, s12, 29
	s_add_i32 s12, s10, s12
	s_ashr_i32 s13, s12, 3
	s_and_b32 s12, s12, -8
	s_sub_i32 s12, s10, s12
	s_cmp_lt_i32 s12, 0
	s_cselect_b32 s16, s14, 0x160
	s_mul_i32 s12, s12, s16
	s_add_i32 s12, s12, s13
	s_mul_hi_i32 s13, s12, 0x2e8ba2e9
	s_lshr_b32 s16, s13, 31
	s_ashr_i32 s13, s13, 3
	s_add_i32 s13, s13, s16
	s_lshl_b32 s16, s13, 1
	s_sub_i32 s17, 0x80, s16
	s_min_i32 s17, s17, 2
	s_abs_i32 s17, s17
	v_cvt_f32_u32_e32 v7, s17
	s_sub_i32 s20, 0, s17
	s_mul_i32 s13, s13, 44
	s_sub_i32 s12, s12, s13
	v_rcp_iflag_f32_e32 v7, v7
	s_ashr_i32 s13, s12, 31
	s_abs_i32 s12, s12
	v_mul_f32_e32 v7, 0x4f7ffffe, v7
	v_cvt_u32_f32_e32 v7, v7
	s_nop 0
	v_readfirstlane_b32 s21, v7
	s_mul_i32 s20, s20, s21
	s_mul_hi_u32 s20, s21, s20
	s_add_i32 s21, s21, s20
	s_mul_hi_u32 s20, s12, s21
	s_mul_i32 s20, s20, s17
	s_sub_i32 s12, s12, s20
	s_sub_i32 s20, s12, s17
	s_cmp_ge_u32 s12, s17
	s_cselect_b32 s12, s20, s12
	s_sub_i32 s20, s12, s17
	s_cmp_ge_u32 s12, s17
	s_cselect_b32 s12, s20, s12
	s_xor_b32 s12, s12, s13
	s_sub_i32 s12, s12, s13
	s_add_i32 s16, s16, s12
	s_and_saveexec_b64 s[12:13], s[6:7]
	v_lshl_add_u32 v112, s16, 8, v4
	v_ashrrev_i32_e32 v113, 31, v112
	v_lshlrev_b64 v[112:113], 6, v[112:113]
	v_lshl_add_u64 v[24:25], s[8:9], 0, v[112:113]
	global_load_dwordx4 v[112:115], v[24:25], off
	global_load_dwordx4 v[116:119], v[24:25], off offset:16
	global_load_dwordx4 v[120:123], v[24:25], off offset:32
	global_load_dwordx4 v[124:127], v[24:25], off offset:48
	s_or_b64 exec, exec, s[12:13]
	s_add_u32 s10, s10, s52
	s_addc_u32 s11, s11, s53
	s_ashr_i32 s12, s10, 31
	s_lshr_b32 s12, s12, 29
	s_add_i32 s12, s10, s12
	s_ashr_i32 s13, s12, 3
	s_and_b32 s12, s12, -8
	s_sub_i32 s12, s10, s12
	s_cmp_lt_i32 s12, 0
	s_cselect_b32 s16, s14, 0x160
	s_mul_i32 s12, s12, s16
	s_add_i32 s12, s12, s13
	s_mul_hi_i32 s13, s12, 0x2e8ba2e9
	s_lshr_b32 s16, s13, 31
	s_ashr_i32 s13, s13, 3
	s_add_i32 s13, s13, s16
	s_lshl_b32 s16, s13, 1
	s_sub_i32 s17, 0x80, s16
	s_min_i32 s17, s17, 2
	s_abs_i32 s17, s17
	v_cvt_f32_u32_e32 v7, s17
	s_sub_i32 s20, 0, s17
	s_mul_i32 s13, s13, 44
	s_sub_i32 s12, s12, s13
	v_rcp_iflag_f32_e32 v7, v7
	s_ashr_i32 s13, s12, 31
	s_abs_i32 s12, s12
	v_mul_f32_e32 v7, 0x4f7ffffe, v7
	v_cvt_u32_f32_e32 v7, v7
	s_nop 0
	v_readfirstlane_b32 s21, v7
	s_mul_i32 s20, s20, s21
	s_mul_hi_u32 s20, s21, s20
	s_add_i32 s21, s21, s20
	s_mul_hi_u32 s20, s12, s21
	s_mul_i32 s20, s20, s17
	s_sub_i32 s12, s12, s20
	s_sub_i32 s20, s12, s17
	s_cmp_ge_u32 s12, s17
	s_cselect_b32 s12, s20, s12
	s_sub_i32 s20, s12, s17
	s_cmp_ge_u32 s12, s17
	s_cselect_b32 s12, s20, s12
	s_xor_b32 s12, s12, s13
	s_sub_i32 s12, s12, s13
; #define LAS __attribute__((address_space(3)))
;     __device__ __forceinline__ bool next(int i, Unit& u) const {
;         const long L = (long)i * G + c; if (L >= nwg) return false;
;         int wgid = (int)L; { const int q = nwg / NXCD, r = nwg % NXCD, xcd = wgid % NXCD, off = wgid / NXCD; wgid = (xcd < r ? xcd * (q + 1) : r * (q + 1) + (xcd - r) * q) + off; }
;         const int nig = WGM * nN, gid = wgid / nig, fm = gid * WGM, gsz = (nM - fm) < WGM ? (nM - fm) : WGM;
;         u.pm = fm + ((wgid % nig) % gsz); u.pn = (wgid % nig) / gsz; u.idx = i; return true;
; __global__ void __launch_bounds__(512, 2) hybrid_fwd(Args args) {
;     ...
;         pg8::Gemm g{XB, Wup, 1024, 1024, 1024, 0, 128, 22}; pg8::StaticOrder S; S.init(128, 22, G, blk);
;         LAS float* rst = (LAS float*)(lds + 139264);
;         { pg8::Unit pu; for (int i = 0; S.next(i, pu); ++i) if (tid < 256) rst[i * 256 + tid] = row_rstd(SSQ + SSQ_STRIDE, pu.pm * 256 + tid);
;           __syncthreads(); }
	s_add_i32 s16, s16, s12
	s_and_saveexec_b64 s[12:13], s[6:7]
	v_lshl_add_u32 v128, s16, 8, v4
	v_ashrrev_i32_e32 v129, 31, v128
	v_lshlrev_b64 v[128:129], 6, v[128:129]
	v_lshl_add_u64 v[24:25], s[8:9], 0, v[128:129]
	global_load_dwordx4 v[128:131], v[24:25], off
	global_load_dwordx4 v[132:135], v[24:25], off offset:16
	global_load_dwordx4 v[136:139], v[24:25], off offset:32
	global_load_dwordx4 v[140:143], v[24:25], off offset:48
	s_or_b64 exec, exec, s[12:13]
	s_add_u32 s10, s10, s52
	s_addc_u32 s11, s11, s53
	s_ashr_i32 s12, s10, 31
	s_lshr_b32 s12, s12, 29
	s_add_i32 s12, s10, s12
	s_ashr_i32 s13, s12, 3
	s_and_b32 s12, s12, -8
	s_sub_i32 s12, s10, s12
	s_cmp_lt_i32 s12, 0
	s_cselect_b32 s16, s14, 0x160
	s_mul_i32 s12, s12, s16
	s_add_i32 s12, s12, s13
	s_mul_hi_i32 s13, s12, 0x2e8ba2e9
	s_lshr_b32 s16, s13, 31
	s_ashr_i32 s13, s13, 3
	s_add_i32 s13, s13, s16
	s_lshl_b32 s16, s13, 1
	s_sub_i32 s17, 0x80, s16
	s_min_i32 s17, s17, 2
	s_abs_i32 s17, s17
	v_cvt_f32_u32_e32 v7, s17
	s_sub_i32 s20, 0, s17
	s_mul_i32 s13, s13, 44
	s_sub_i32 s12, s12, s13
	v_rcp_iflag_f32_e32 v7, v7
	s_ashr_i32 s13, s12, 31
	s_abs_i32 s12, s12
	v_mul_f32_e32 v7, 0x4f7ffffe, v7
	v_cvt_u32_f32_e32 v7, v7
	s_nop 0
	v_readfirstlane_b32 s21, v7
	s_mul_i32 s20, s20, s21
	s_mul_hi_u32 s20, s21, s20
	s_add_i32 s21, s21, s20
	s_mul_hi_u32 s20, s12, s21
	s_mul_i32 s20, s20, s17
	s_sub_i32 s12, s12, s20
	s_sub_i32 s20, s12, s17
	s_cmp_ge_u32 s12, s17
	s_cselect_b32 s12, s20, s12
	s_sub_i32 s20, s12, s17
	s_cmp_ge_u32 s12, s17
	s_cselect_b32 s12, s20, s12
	s_xor_b32 s12, s12, s13
	s_sub_i32 s12, s12, s13
	s_add_i32 s16, s16, s12
	s_and_saveexec_b64 s[12:13], s[6:7]
	v_lshl_add_u32 v144, s16, 8, v4
	v_ashrrev_i32_e32 v145, 31, v144
	v_lshlrev_b64 v[144:145], 6, v[144:145]
	v_lshl_add_u64 v[24:25], s[8:9], 0, v[144:145]
	global_load_dwordx4 v[144:147], v[24:25], off
	global_load_dwordx4 v[148:151], v[24:25], off offset:16
	global_load_dwordx4 v[152:155], v[24:25], off offset:32
	global_load_dwordx4 v[156:159], v[24:25], off offset:48
	s_or_b64 exec, exec, s[12:13]
	s_add_u32 s10, s10, s52
	s_addc_u32 s11, s11, s53
	s_ashr_i32 s12, s10, 31
	s_lshr_b32 s12, s12, 29
	s_add_i32 s12, s10, s12
	s_ashr_i32 s13, s12, 3
	s_and_b32 s12, s12, -8
	s_sub_i32 s12, s10, s12
	s_cmp_lt_i32 s12, 0
	s_cselect_b32 s16, s14, 0x160
	s_mul_i32 s12, s12, s16
	s_add_i32 s12, s12, s13
	s_mul_hi_i32 s13, s12, 0x2e8ba2e9
	s_lshr_b32 s16, s13, 31
	s_ashr_i32 s13, s13, 3
	s_add_i32 s13, s13, s16
	s_lshl_b32 s16, s13, 1
	s_sub_i32 s17, 0x80, s16
	s_min_i32 s17, s17, 2
	s_abs_i32 s17, s17
	v_cvt_f32_u32_e32 v7, s17
	s_sub_i32 s20, 0, s17
	s_mul_i32 s13, s13, 44
	s_sub_i32 s12, s12, s13
	v_rcp_iflag_f32_e32 v7, v7
	s_ashr_i32 s13, s12, 31
	s_abs_i32 s12, s12
	v_mul_f32_e32 v7, 0x4f7ffffe, v7
	v_cvt_u32_f32_e32 v7, v7
	s_nop 0
	v_readfirstlane_b32 s21, v7
	s_mul_i32 s20, s20, s21
	s_mul_hi_u32 s20, s21, s20
	s_add_i32 s21, s21, s20
	s_mul_hi_u32 s20, s12, s21
	s_mul_i32 s20, s20, s17
	s_sub_i32 s12, s12, s20
	s_sub_i32 s20, s12, s17
	s_cmp_ge_u32 s12, s17
	s_cselect_b32 s12, s20, s12
	s_sub_i32 s20, s12, s17
	s_cmp_ge_u32 s12, s17
	s_cselect_b32 s12, s20, s12
	s_xor_b32 s12, s12, s13
	s_sub_i32 s12, s12, s13
	s_add_i32 s16, s16, s12
	s_and_saveexec_b64 s[12:13], s[6:7]
	v_lshl_add_u32 v160, s16, 8, v4
	v_ashrrev_i32_e32 v161, 31, v160
	v_lshlrev_b64 v[160:161], 6, v[160:161]
	v_lshl_add_u64 v[24:25], s[8:9], 0, v[160:161]
	global_load_dwordx4 v[160:163], v[24:25], off
	global_load_dwordx4 v[164:167], v[24:25], off offset:16
	global_load_dwordx4 v[168:171], v[24:25], off offset:32
	global_load_dwordx4 v[172:175], v[24:25], off offset:48
	s_or_b64 exec, exec, s[12:13]
	s_add_u32 s10, s10, s52
	s_addc_u32 s11, s11, s53
	s_ashr_i32 s12, s10, 31
	s_lshr_b32 s12, s12, 29
	s_add_i32 s12, s10, s12
	s_ashr_i32 s13, s12, 3
	s_and_b32 s12, s12, -8
	s_sub_i32 s12, s10, s12
	s_cmp_lt_i32 s12, 0
	s_cselect_b32 s16, s14, 0x160
	s_mul_i32 s12, s12, s16
	s_add_i32 s12, s12, s13
	s_mul_hi_i32 s13, s12, 0x2e8ba2e9
	s_lshr_b32 s16, s13, 31
	s_ashr_i32 s13, s13, 3
	s_add_i32 s13, s13, s16
	s_lshl_b32 s16, s13, 1
	s_sub_i32 s17, 0x80, s16
	s_min_i32 s17, s17, 2
	s_abs_i32 s17, s17
	v_cvt_f32_u32_e32 v7, s17
	s_sub_i32 s20, 0, s17
	s_mul_i32 s13, s13, 44
	s_sub_i32 s12, s12, s13
	v_rcp_iflag_f32_e32 v7, v7
	s_ashr_i32 s13, s12, 31
	s_abs_i32 s12, s12
	v_mul_f32_e32 v7, 0x4f7ffffe, v7
	v_cvt_u32_f32_e32 v7, v7
	s_nop 0
	v_readfirstlane_b32 s21, v7
	s_mul_i32 s20, s20, s21
	s_mul_hi_u32 s20, s21, s20
	s_add_i32 s21, s21, s20
	s_mul_hi_u32 s20, s12, s21
	s_mul_i32 s20, s20, s17
	s_sub_i32 s12, s12, s20
	s_sub_i32 s20, s12, s17
	s_cmp_ge_u32 s12, s17
	s_cselect_b32 s12, s20, s12
	s_sub_i32 s20, s12, s17
	s_cmp_ge_u32 s12, s17
	s_cselect_b32 s12, s20, s12
	s_xor_b32 s12, s12, s13
	s_sub_i32 s12, s12, s13
	s_add_i32 s16, s16, s12
	s_and_saveexec_b64 s[12:13], s[6:7]
	v_lshl_add_u32 v176, s16, 8, v4
	v_ashrrev_i32_e32 v177, 31, v176
	v_lshlrev_b64 v[176:177], 6, v[176:177]
	v_lshl_add_u64 v[24:25], s[8:9], 0, v[176:177]
	global_load_dwordx4 v[176:179], v[24:25], off
	global_load_dwordx4 v[180:183], v[24:25], off offset:16
	global_load_dwordx4 v[184:187], v[24:25], off offset:32
	global_load_dwordx4 v[188:191], v[24:25], off offset:48
	s_or_b64 exec, exec, s[12:13]
	s_add_u32 s10, s10, s52
	s_addc_u32 s11, s11, s53
	s_ashr_i32 s12, s10, 31
	s_lshr_b32 s12, s12, 29
	s_add_i32 s12, s10, s12
	s_ashr_i32 s13, s12, 3
	s_and_b32 s12, s12, -8
	s_sub_i32 s12, s10, s12
	s_cmp_lt_i32 s12, 0
	s_cselect_b32 s16, s14, 0x160
	s_mul_i32 s12, s12, s16
	s_add_i32 s12, s12, s13
	s_mul_hi_i32 s13, s12, 0x2e8ba2e9
	s_lshr_b32 s16, s13, 31
	s_ashr_i32 s13, s13, 3
	s_add_i32 s13, s13, s16
	s_lshl_b32 s16, s13, 1
	s_sub_i32 s17, 0x80, s16
	s_min_i32 s17, s17, 2
	s_abs_i32 s17, s17
	v_cvt_f32_u32_e32 v7, s17
	s_sub_i32 s20, 0, s17
	s_mul_i32 s13, s13, 44
	s_sub_i32 s12, s12, s13
	v_rcp_iflag_f32_e32 v7, v7
	s_ashr_i32 s13, s12, 31
	s_abs_i32 s12, s12
	v_mul_f32_e32 v7, 0x4f7ffffe, v7
	v_cvt_u32_f32_e32 v7, v7
	s_nop 0
	v_readfirstlane_b32 s21, v7
	s_mul_i32 s20, s20, s21
	s_mul_hi_u32 s20, s21, s20
	s_add_i32 s21, s21, s20
	s_mul_hi_u32 s20, s12, s21
	s_mul_i32 s20, s20, s17
	s_sub_i32 s12, s12, s20
	s_sub_i32 s20, s12, s17
	s_cmp_ge_u32 s12, s17
	s_cselect_b32 s12, s20, s12
	s_sub_i32 s20, s12, s17
	s_cmp_ge_u32 s12, s17
	s_cselect_b32 s12, s20, s12
	s_xor_b32 s12, s12, s13
	s_sub_i32 s12, s12, s13
	s_add_i32 s16, s16, s12
	s_and_saveexec_b64 s[12:13], s[6:7]
	v_lshl_add_u32 v192, s16, 8, v4
	v_ashrrev_i32_e32 v193, 31, v192
	v_lshlrev_b64 v[192:193], 6, v[192:193]
	v_lshl_add_u64 v[24:25], s[8:9], 0, v[192:193]
	global_load_dwordx4 v[192:195], v[24:25], off
	global_load_dwordx4 v[196:199], v[24:25], off offset:16
	global_load_dwordx4 v[200:203], v[24:25], off offset:32
	global_load_dwordx4 v[204:207], v[24:25], off offset:48
	s_or_b64 exec, exec, s[12:13]
	s_and_saveexec_b64 s[12:13], s[6:7]
	s_waitcnt vmcnt(0)
; __device__ __forceinline__ float row_rstd(const float* ssq, int row) {
;     const f32x4* p = (const f32x4*)(ssq + (size_t)row * 16);
;     const f32x4 a = p[0], b = p[1], c = p[2], d = p[3];
;     const float s = ((a[0] + a[1]) + (a[2] + a[3])) + ((b[0] + b[1]) + (b[2] + b[3])) + ((c[0] + c[1]) + (c[2] + c[3])) + ((d[0] + d[1]) + (d[2] + d[3]));
;     return rsqrtf(s * (1.0f / 1024.0f) + EPS);
; }
; __global__ void __launch_bounds__(512, 2) hybrid_fwd(Args args) {
;     ...
;         { pg8::Unit pu; for (int i = 0; S.next(i, pu); ++i) if (tid < 256) rst[i * 256 + tid] = row_rstd(SSQ + SSQ_STRIDE, pu.pm * 256 + tid);
	v_mov_b32_e32 v24, v33
	v_mov_b32_e32 v25, v34
	v_mov_b32_e32 v33, v35
	v_mov_b32_e32 v34, v37
	v_mov_b32_e32 v35, v38
	v_mov_b32_e32 v37, v39
	v_pk_add_f32 v[32:33], v[24:25], v[32:33]
	v_pk_add_f32 v[34:35], v[34:35], v[36:37]
	v_pk_add_f32 v[32:33], v[32:33], v[32:33] op_sel:[0,1] op_sel_hi:[1,0]
	v_pk_add_f32 v[34:35], v[34:35], v[34:35] op_sel:[0,1] op_sel_hi:[1,0]
	v_add_f32_e32 v38, v40, v41
	v_add_f32_e32 v40, v42, v43
	v_mov_b32_e32 v39, v46
	v_mov_b32_e32 v41, v47
	v_mov_b32_e32 v33, v44
	v_mov_b32_e32 v35, v45
	v_pk_add_f32 v[36:37], v[38:39], v[40:41]
	v_pk_add_f32 v[32:33], v[32:33], v[34:35]
	s_nop 0
	v_pk_add_f32 v[32:33], v[32:33], v[36:37]
	s_nop 0
	v_add_f32_e32 v7, v32, v33
	v_fmamk_f32 v7, v7, 0x3a800000, v6
	v_mul_f32_e32 v32, 0x4b800000, v7
	v_cmp_gt_f32_e32 vcc, s15, v7
	s_nop 1
	v_cndmask_b32_e32 v7, v7, v32, vcc
	v_rsq_f32_e32 v7, v7
	s_nop 0
	v_mul_f32_e32 v32, 0x45800000, v7
	v_cndmask_b32_e32 v7, v7, v32, vcc
	ds_write_b32 v5, v7
	v_mov_b32_e32 v24, v49
	v_mov_b32_e32 v25, v50
	v_mov_b32_e32 v49, v51
	v_mov_b32_e32 v50, v53
	v_mov_b32_e32 v51, v54
	v_mov_b32_e32 v53, v55
	v_pk_add_f32 v[48:49], v[24:25], v[48:49]
	v_pk_add_f32 v[50:51], v[50:51], v[52:53]
	v_pk_add_f32 v[48:49], v[48:49], v[48:49] op_sel:[0,1] op_sel_hi:[1,0]
	v_pk_add_f32 v[50:51], v[50:51], v[50:51] op_sel:[0,1] op_sel_hi:[1,0]
	v_add_f32_e32 v54, v56, v57
	v_add_f32_e32 v56, v58, v59
	v_mov_b32_e32 v55, v62
	v_mov_b32_e32 v57, v63
	v_mov_b32_e32 v49, v60
	v_mov_b32_e32 v51, v61
	v_pk_add_f32 v[52:53], v[54:55], v[56:57]
	v_pk_add_f32 v[48:49], v[48:49], v[50:51]
	s_nop 0
	v_pk_add_f32 v[48:49], v[48:49], v[52:53]
	s_nop 0
	v_add_f32_e32 v7, v48, v49
	v_fmamk_f32 v7, v7, 0x3a800000, v6
	v_mul_f32_e32 v48, 0x4b800000, v7
	v_cmp_gt_f32_e32 vcc, s15, v7
	s_nop 1
	v_cndmask_b32_e32 v7, v7, v48, vcc
	v_rsq_f32_e32 v7, v7
	s_nop 0
	v_mul_f32_e32 v48, 0x45800000, v7
	v_cndmask_b32_e32 v7, v7, v48, vcc
	ds_write_b32 v5, v7 offset:1024
	v_mov_b32_e32 v24, v65
	v_mov_b32_e32 v25, v66
	v_mov_b32_e32 v65, v67
	v_mov_b32_e32 v66, v69
	v_mov_b32_e32 v67, v70
	v_mov_b32_e32 v69, v71
	v_pk_add_f32 v[64:65], v[24:25], v[64:65]
	v_pk_add_f32 v[66:67], v[66:67], v[68:69]
	v_pk_add_f32 v[64:65], v[64:65], v[64:65] op_sel:[0,1] op_sel_hi:[1,0]
	v_pk_add_f32 v[66:67], v[66:67], v[66:67] op_sel:[0,1] op_sel_hi:[1,0]
	v_add_f32_e32 v70, v72, v73
	v_add_f32_e32 v72, v74, v75
	v_mov_b32_e32 v71, v78
	v_mov_b32_e32 v73, v79
	v_mov_b32_e32 v65, v76
	v_mov_b32_e32 v67, v77
	v_pk_add_f32 v[68:69], v[70:71], v[72:73]
	v_pk_add_f32 v[64:65], v[64:65], v[66:67]
	s_nop 0
	v_pk_add_f32 v[64:65], v[64:65], v[68:69]
	s_nop 0
	v_add_f32_e32 v7, v64, v65
	v_fmamk_f32 v7, v7, 0x3a800000, v6
	v_mul_f32_e32 v64, 0x4b800000, v7
	v_cmp_gt_f32_e32 vcc, s15, v7
	s_nop 1
	v_cndmask_b32_e32 v7, v7, v64, vcc
	v_rsq_f32_e32 v7, v7
	s_nop 0
	v_mul_f32_e32 v64, 0x45800000, v7
	v_cndmask_b32_e32 v7, v7, v64, vcc
	ds_write_b32 v5, v7 offset:2048
	v_mov_b32_e32 v24, v81
	v_mov_b32_e32 v25, v82
	v_mov_b32_e32 v81, v83
	v_mov_b32_e32 v82, v85
	v_mov_b32_e32 v83, v86
	v_mov_b32_e32 v85, v87
	v_pk_add_f32 v[80:81], v[24:25], v[80:81]
	v_pk_add_f32 v[82:83], v[82:83], v[84:85]
	v_pk_add_f32 v[80:81], v[80:81], v[80:81] op_sel:[0,1] op_sel_hi:[1,0]
	v_pk_add_f32 v[82:83], v[82:83], v[82:83] op_sel:[0,1] op_sel_hi:[1,0]
	v_add_f32_e32 v86, v88, v89
	v_add_f32_e32 v88, v90, v91
	v_mov_b32_e32 v87, v94
	v_mov_b32_e32 v89, v95
	v_mov_b32_e32 v81, v92
	v_mov_b32_e32 v83, v93
	v_pk_add_f32 v[84:85], v[86:87], v[88:89]
	v_pk_add_f32 v[80:81], v[80:81], v[82:83]
	s_nop 0
	v_pk_add_f32 v[80:81], v[80:81], v[84:85]
	s_nop 0
	v_add_f32_e32 v7, v80, v81
	v_fmamk_f32 v7, v7, 0x3a800000, v6
	v_mul_f32_e32 v80, 0x4b800000, v7
	v_cmp_gt_f32_e32 vcc, s15, v7
	s_nop 1
	v_cndmask_b32_e32 v7, v7, v80, vcc
	v_rsq_f32_e32 v7, v7
	s_nop 0
	v_mul_f32_e32 v80, 0x45800000, v7
	v_cndmask_b32_e32 v7, v7, v80, vcc
	ds_write_b32 v5, v7 offset:3072
	v_mov_b32_e32 v24, v97
	v_mov_b32_e32 v25, v98
	v_mov_b32_e32 v97, v99
	v_mov_b32_e32 v98, v101
	v_mov_b32_e32 v99, v102
	v_mov_b32_e32 v101, v103
	v_pk_add_f32 v[96:97], v[24:25], v[96:97]
	v_pk_add_f32 v[98:99], v[98:99], v[100:101]
	v_pk_add_f32 v[96:97], v[96:97], v[96:97] op_sel:[0,1] op_sel_hi:[1,0]
	v_pk_add_f32 v[98:99], v[98:99], v[98:99] op_sel:[0,1] op_sel_hi:[1,0]
	v_add_f32_e32 v102, v104, v105
	v_add_f32_e32 v104, v106, v107
	v_mov_b32_e32 v103, v110
	v_mov_b32_e32 v105, v111
	v_mov_b32_e32 v97, v108
	v_mov_b32_e32 v99, v109
	v_pk_add_f32 v[100:101], v[102:103], v[104:105]
	v_pk_add_f32 v[96:97], v[96:97], v[98:99]
	s_nop 0
	v_pk_add_f32 v[96:97], v[96:97], v[100:101]
	s_nop 0
	v_add_f32_e32 v7, v96, v97
	v_fmamk_f32 v7, v7, 0x3a800000, v6
	v_mul_f32_e32 v96, 0x4b800000, v7
	v_cmp_gt_f32_e32 vcc, s15, v7
	s_nop 1
	v_cndmask_b32_e32 v7, v7, v96, vcc
	v_rsq_f32_e32 v7, v7
	s_nop 0
	v_mul_f32_e32 v96, 0x45800000, v7
	v_cndmask_b32_e32 v7, v7, v96, vcc
	ds_write_b32 v5, v7 offset:4096
	v_mov_b32_e32 v24, v113
	v_mov_b32_e32 v25, v114
	v_mov_b32_e32 v113, v115
	v_mov_b32_e32 v114, v117
	v_mov_b32_e32 v115, v118
	v_mov_b32_e32 v117, v119
	v_pk_add_f32 v[112:113], v[24:25], v[112:113]
	v_pk_add_f32 v[114:115], v[114:115], v[116:117]
	v_pk_add_f32 v[112:113], v[112:113], v[112:113] op_sel:[0,1] op_sel_hi:[1,0]
	v_pk_add_f32 v[114:115], v[114:115], v[114:115] op_sel:[0,1] op_sel_hi:[1,0]
	v_add_f32_e32 v118, v120, v121
	v_add_f32_e32 v120, v122, v123
	v_mov_b32_e32 v119, v126
	v_mov_b32_e32 v121, v127
	v_mov_b32_e32 v113, v124
	v_mov_b32_e32 v115, v125
	v_pk_add_f32 v[116:117], v[118:119], v[120:121]
	v_pk_add_f32 v[112:113], v[112:113], v[114:115]
	s_nop 0
; __device__ __forceinline__ float row_rstd(const float* ssq, int row) {
;     const f32x4* p = (const f32x4*)(ssq + (size_t)row * 16);
;     const f32x4 a = p[0], b = p[1], c = p[2], d = p[3];
;     const float s = ((a[0] + a[1]) + (a[2] + a[3])) + ((b[0] + b[1]) + (b[2] + b[3])) + ((c[0] + c[1]) + (c[2] + c[3])) + ((d[0] + d[1]) + (d[2] + d[3]));
;     return rsqrtf(s * (1.0f / 1024.0f) + EPS);
; }
; __global__ void __launch_bounds__(512, 2) hybrid_fwd(Args args) {
;     ...
;         { pg8::Unit pu; for (int i = 0; S.next(i, pu); ++i) if (tid < 256) rst[i * 256 + tid] = row_rstd(SSQ + SSQ_STRIDE, pu.pm * 256 + tid);
	v_pk_add_f32 v[112:113], v[112:113], v[116:117]
	s_nop 0
	v_add_f32_e32 v7, v112, v113
	v_fmamk_f32 v7, v7, 0x3a800000, v6
	v_mul_f32_e32 v112, 0x4b800000, v7
	v_cmp_gt_f32_e32 vcc, s15, v7
	s_nop 1
	v_cndmask_b32_e32 v7, v7, v112, vcc
	v_rsq_f32_e32 v7, v7
	s_nop 0
	v_mul_f32_e32 v112, 0x45800000, v7
	v_cndmask_b32_e32 v7, v7, v112, vcc
	ds_write_b32 v5, v7 offset:5120
	v_mov_b32_e32 v24, v129
	v_mov_b32_e32 v25, v130
	v_mov_b32_e32 v129, v131
	v_mov_b32_e32 v130, v133
	v_mov_b32_e32 v131, v134
	v_mov_b32_e32 v133, v135
	v_pk_add_f32 v[128:129], v[24:25], v[128:129]
	v_pk_add_f32 v[130:131], v[130:131], v[132:133]
	v_pk_add_f32 v[128:129], v[128:129], v[128:129] op_sel:[0,1] op_sel_hi:[1,0]
	v_pk_add_f32 v[130:131], v[130:131], v[130:131] op_sel:[0,1] op_sel_hi:[1,0]
	v_add_f32_e32 v134, v136, v137
	v_add_f32_e32 v136, v138, v139
	v_mov_b32_e32 v135, v142
	v_mov_b32_e32 v137, v143
	v_mov_b32_e32 v129, v140
	v_mov_b32_e32 v131, v141
	v_pk_add_f32 v[132:133], v[134:135], v[136:137]
	v_pk_add_f32 v[128:129], v[128:129], v[130:131]
	s_nop 0
	v_pk_add_f32 v[128:129], v[128:129], v[132:133]
	s_nop 0
	v_add_f32_e32 v7, v128, v129
	v_fmamk_f32 v7, v7, 0x3a800000, v6
	v_mul_f32_e32 v128, 0x4b800000, v7
	v_cmp_gt_f32_e32 vcc, s15, v7
	s_nop 1
	v_cndmask_b32_e32 v7, v7, v128, vcc
	v_rsq_f32_e32 v7, v7
	s_nop 0
	v_mul_f32_e32 v128, 0x45800000, v7
	v_cndmask_b32_e32 v7, v7, v128, vcc
	ds_write_b32 v5, v7 offset:6144
	v_mov_b32_e32 v24, v145
	v_mov_b32_e32 v25, v146
	v_mov_b32_e32 v145, v147
	v_mov_b32_e32 v146, v149
	v_mov_b32_e32 v147, v150
	v_mov_b32_e32 v149, v151
	v_pk_add_f32 v[144:145], v[24:25], v[144:145]
	v_pk_add_f32 v[146:147], v[146:147], v[148:149]
	v_pk_add_f32 v[144:145], v[144:145], v[144:145] op_sel:[0,1] op_sel_hi:[1,0]
	v_pk_add_f32 v[146:147], v[146:147], v[146:147] op_sel:[0,1] op_sel_hi:[1,0]
	v_add_f32_e32 v150, v152, v153
	v_add_f32_e32 v152, v154, v155
	v_mov_b32_e32 v151, v158
	v_mov_b32_e32 v153, v159
	v_mov_b32_e32 v145, v156
	v_mov_b32_e32 v147, v157
	v_pk_add_f32 v[148:149], v[150:151], v[152:153]
	v_pk_add_f32 v[144:145], v[144:145], v[146:147]
	s_nop 0
	v_pk_add_f32 v[144:145], v[144:145], v[148:149]
	s_nop 0
	v_add_f32_e32 v7, v144, v145
	v_fmamk_f32 v7, v7, 0x3a800000, v6
	v_mul_f32_e32 v144, 0x4b800000, v7
	v_cmp_gt_f32_e32 vcc, s15, v7
	s_nop 1
	v_cndmask_b32_e32 v7, v7, v144, vcc
	v_rsq_f32_e32 v7, v7
	s_nop 0
	v_mul_f32_e32 v144, 0x45800000, v7
	v_cndmask_b32_e32 v7, v7, v144, vcc
	ds_write_b32 v5, v7 offset:7168
	v_mov_b32_e32 v24, v161
	v_mov_b32_e32 v25, v162
	v_mov_b32_e32 v161, v163
	v_mov_b32_e32 v162, v165
	v_mov_b32_e32 v163, v166
	v_mov_b32_e32 v165, v167
	v_pk_add_f32 v[160:161], v[24:25], v[160:161]
	v_pk_add_f32 v[162:163], v[162:163], v[164:165]
	v_pk_add_f32 v[160:161], v[160:161], v[160:161] op_sel:[0,1] op_sel_hi:[1,0]
	v_pk_add_f32 v[162:163], v[162:163], v[162:163] op_sel:[0,1] op_sel_hi:[1,0]
	v_add_f32_e32 v166, v168, v169
	v_add_f32_e32 v168, v170, v171
	v_mov_b32_e32 v167, v174
	v_mov_b32_e32 v169, v175
	v_mov_b32_e32 v161, v172
	v_mov_b32_e32 v163, v173
	v_pk_add_f32 v[164:165], v[166:167], v[168:169]
	v_pk_add_f32 v[160:161], v[160:161], v[162:163]
	s_nop 0
	v_pk_add_f32 v[160:161], v[160:161], v[164:165]
	s_nop 0
	v_add_f32_e32 v7, v160, v161
	v_fmamk_f32 v7, v7, 0x3a800000, v6
	v_mul_f32_e32 v160, 0x4b800000, v7
	v_cmp_gt_f32_e32 vcc, s15, v7
	s_nop 1
	v_cndmask_b32_e32 v7, v7, v160, vcc
	v_rsq_f32_e32 v7, v7
	s_nop 0
	v_mul_f32_e32 v160, 0x45800000, v7
	v_cndmask_b32_e32 v7, v7, v160, vcc
	ds_write_b32 v5, v7 offset:8192
	v_mov_b32_e32 v24, v177
	v_mov_b32_e32 v25, v178
	v_mov_b32_e32 v177, v179
	v_mov_b32_e32 v178, v181
	v_mov_b32_e32 v179, v182
	v_mov_b32_e32 v181, v183
	v_pk_add_f32 v[176:177], v[24:25], v[176:177]
	v_pk_add_f32 v[178:179], v[178:179], v[180:181]
	v_pk_add_f32 v[176:177], v[176:177], v[176:177] op_sel:[0,1] op_sel_hi:[1,0]
	v_pk_add_f32 v[178:179], v[178:179], v[178:179] op_sel:[0,1] op_sel_hi:[1,0]
	v_add_f32_e32 v182, v184, v185
	v_add_f32_e32 v184, v186, v187
	v_mov_b32_e32 v183, v190
	v_mov_b32_e32 v185, v191
	v_mov_b32_e32 v177, v188
	v_mov_b32_e32 v179, v189
	v_pk_add_f32 v[180:181], v[182:183], v[184:185]
	v_pk_add_f32 v[176:177], v[176:177], v[178:179]
	s_nop 0
	v_pk_add_f32 v[176:177], v[176:177], v[180:181]
	s_nop 0
	v_add_f32_e32 v7, v176, v177
	v_fmamk_f32 v7, v7, 0x3a800000, v6
	v_mul_f32_e32 v176, 0x4b800000, v7
	v_cmp_gt_f32_e32 vcc, s15, v7
	s_nop 1
	v_cndmask_b32_e32 v7, v7, v176, vcc
	v_rsq_f32_e32 v7, v7
	s_nop 0
	v_mul_f32_e32 v176, 0x45800000, v7
	v_cndmask_b32_e32 v7, v7, v176, vcc
	ds_write_b32 v5, v7 offset:9216
	v_mov_b32_e32 v24, v193
	v_mov_b32_e32 v25, v194
	v_mov_b32_e32 v193, v195
	v_mov_b32_e32 v194, v197
	v_mov_b32_e32 v195, v198
	v_mov_b32_e32 v197, v199
	v_pk_add_f32 v[192:193], v[24:25], v[192:193]
	v_pk_add_f32 v[194:195], v[194:195], v[196:197]
	v_pk_add_f32 v[192:193], v[192:193], v[192:193] op_sel:[0,1] op_sel_hi:[1,0]
	v_pk_add_f32 v[194:195], v[194:195], v[194:195] op_sel:[0,1] op_sel_hi:[1,0]
	v_add_f32_e32 v198, v200, v201
	v_add_f32_e32 v200, v202, v203
	v_mov_b32_e32 v199, v206
	v_mov_b32_e32 v201, v207
	v_mov_b32_e32 v193, v204
	v_mov_b32_e32 v195, v205
	v_pk_add_f32 v[196:197], v[198:199], v[200:201]
	v_pk_add_f32 v[192:193], v[192:193], v[194:195]
	s_nop 0
	v_pk_add_f32 v[192:193], v[192:193], v[196:197]
	s_nop 0
	v_add_f32_e32 v7, v192, v193
	v_fmamk_f32 v7, v7, 0x3a800000, v6
	v_mul_f32_e32 v192, 0x4b800000, v7
	v_cmp_gt_f32_e32 vcc, s15, v7
	s_nop 1
	v_cndmask_b32_e32 v7, v7, v192, vcc
	v_rsq_f32_e32 v7, v7
	s_nop 0
	v_mul_f32_e32 v192, 0x45800000, v7
	v_cndmask_b32_e32 v7, v7, v192, vcc
	ds_write_b32 v5, v7 offset:10240
	s_or_b64 exec, exec, s[12:13]
	s_branch .LBB0_585

; #define LAS __attribute__((address_space(3)))
;     __device__ __forceinline__ bool next(int i, Unit& u) const {
;         const long L = (long)i * G + c; if (L >= nwg) return false;
;         int wgid = (int)L; { const int q = nwg / NXCD, r = nwg % NXCD, xcd = wgid % NXCD, off = wgid / NXCD; wgid = (xcd < r ? xcd * (q + 1) : r * (q + 1) + (xcd - r) * q) + off; }
;         const int nig = WGM * nN, gid = wgid / nig, fm = gid * WGM, gsz = (nM - fm) < WGM ? (nM - fm) : WGM;
;         u.pm = fm + ((wgid % nig) % gsz); u.pn = (wgid % nig) / gsz; u.idx = i; return true;
; __global__ void __launch_bounds__(512, 2) hybrid_fwd(Args args) {
;     ...
;         pg8::Gemm g{XB, WinO, 1024, 1024, 1024, 0, 128, 12}; pg8::StaticOrder S; S.init(128, 12, G, blk);
;         LAS float* rst = (LAS float*)(lds + 139264);
;         { pg8::Unit pu; for (int i = 0; S.next(i, pu); ++i) if (tid < 256) rst[i * 256 + tid] = row_rstd(SSQ + 2 * SSQ_STRIDE, pu.pm * 256 + tid);
;           __syncthreads(); }
.LBB0_804:
	s_cmp_lt_i32 s82, 8
	s_cselect_b64 s[8:9], -1, 0
	s_and_b64 s[14:15], s[8:9], s[6:7]
	s_andn2_b64 vcc, exec, s[14:15]
	s_cbranch_vccnz .LBB0_919
	v_mov_b32_e32 v4, v220
	s_load_dword s54, s[0:1], 0xb0
	s_waitcnt lgkmcnt(0)
	s_ashr_i32 s3, s2, 31
	s_movk_i32 s6, 0x100
	v_lshl_add_u32 v0, v4, 2, 0
	v_cmp_gt_i32_e64 s[6:7], s6, v4
	s_ashr_i32 s55, s54, 31
	s_add_u32 s8, s80, 0x3800000
	s_addc_u32 s9, s81, 0
	v_add_u32_e32 v5, 0x22000, v0
	v_mov_b64_e32 v[0:1], 0x600
	v_mov_b64_e32 v[2:3], 0x5ff
	s_movk_i32 s16, 0xc1
	v_mov_b32_e32 v6, 0x358637bd
	s_mov_b32 s17, 0x800000
	s_mov_b64 s[10:11], s[2:3]
	s_cmp_lg_u32 s54, 0x100
	s_cbranch_scc1 .Lrs2_slow
	s_ashr_i32 s12, s10, 31
	s_lshr_b32 s12, s12, 29
	s_add_i32 s12, s10, s12
	s_ashr_i32 s13, s12, 3
	s_and_b32 s12, s12, -8
	s_sub_i32 s12, s10, s12
	s_cmp_lt_i32 s12, 0
	s_cselect_b32 s18, s16, 0xc0
	s_mul_i32 s12, s12, s18
	s_add_i32 s12, s12, s13
	s_mul_hi_i32 s13, s12, 0x2aaaaaab
	s_lshr_b32 s18, s13, 31
	s_ashr_i32 s13, s13, 2
	s_add_i32 s13, s13, s18
	s_lshl_b32 s18, s13, 1
	s_sub_i32 s19, 0x80, s18
	s_min_i32 s19, s19, 2
	s_abs_i32 s19, s19
	v_cvt_f32_u32_e32 v7, s19
	s_sub_i32 s20, 0, s19
	s_mul_i32 s13, s13, 24
	s_sub_i32 s12, s12, s13
	v_rcp_iflag_f32_e32 v7, v7
	s_ashr_i32 s13, s12, 31
	s_abs_i32 s12, s12
	v_mul_f32_e32 v7, 0x4f7ffffe, v7
	v_cvt_u32_f32_e32 v7, v7
	s_nop 0
	v_readfirstlane_b32 s21, v7
	s_mul_i32 s20, s20, s21
	s_mul_hi_u32 s20, s21, s20
	s_add_i32 s21, s21, s20
	s_mul_hi_u32 s20, s12, s21
	s_mul_i32 s20, s20, s19
	s_sub_i32 s12, s12, s20
	s_sub_i32 s20, s12, s19
	s_cmp_ge_u32 s12, s19
	s_cselect_b32 s12, s20, s12
	s_sub_i32 s20, s12, s19
	s_cmp_ge_u32 s12, s19
	s_cselect_b32 s12, s20, s12
	s_xor_b32 s12, s12, s13
	s_sub_i32 s12, s12, s13
	s_add_i32 s18, s18, s12
	s_and_saveexec_b64 s[12:13], s[6:7]
	v_lshl_add_u32 v32, s18, 8, v4
	v_ashrrev_i32_e32 v33, 31, v32
	v_lshlrev_b64 v[32:33], 6, v[32:33]
	v_lshl_add_u64 v[24:25], s[8:9], 0, v[32:33]
	global_load_dwordx4 v[32:35], v[24:25], off
	global_load_dwordx4 v[36:39], v[24:25], off offset:16
	global_load_dwordx4 v[40:43], v[24:25], off offset:32
	global_load_dwordx4 v[44:47], v[24:25], off offset:48
	s_or_b64 exec, exec, s[12:13]
	s_add_u32 s10, s10, s54
	s_addc_u32 s11, s11, s55
	s_ashr_i32 s12, s10, 31
	s_lshr_b32 s12, s12, 29
	s_add_i32 s12, s10, s12
	s_ashr_i32 s13, s12, 3
	s_and_b32 s12, s12, -8
	s_sub_i32 s12, s10, s12
	s_cmp_lt_i32 s12, 0
	s_cselect_b32 s18, s16, 0xc0
	s_mul_i32 s12, s12, s18
	s_add_i32 s12, s12, s13
	s_mul_hi_i32 s13, s12, 0x2aaaaaab
	s_lshr_b32 s18, s13, 31
	s_ashr_i32 s13, s13, 2
	s_add_i32 s13, s13, s18
	s_lshl_b32 s18, s13, 1
	s_sub_i32 s19, 0x80, s18
	s_min_i32 s19, s19, 2
	s_abs_i32 s19, s19
	v_cvt_f32_u32_e32 v7, s19
	s_sub_i32 s20, 0, s19
	s_mul_i32 s13, s13, 24
	s_sub_i32 s12, s12, s13
	v_rcp_iflag_f32_e32 v7, v7
	s_ashr_i32 s13, s12, 31
	s_abs_i32 s12, s12
	v_mul_f32_e32 v7, 0x4f7ffffe, v7
	v_cvt_u32_f32_e32 v7, v7
	s_nop 0
	v_readfirstlane_b32 s21, v7
	s_mul_i32 s20, s20, s21
	s_mul_hi_u32 s20, s21, s20
	s_add_i32 s21, s21, s20
	s_mul_hi_u32 s20, s12, s21
	s_mul_i32 s20, s20, s19
	s_sub_i32 s12, s12, s20
	s_sub_i32 s20, s12, s19
	s_cmp_ge_u32 s12, s19
	s_cselect_b32 s12, s20, s12
	s_sub_i32 s20, s12, s19
	s_cmp_ge_u32 s12, s19
	s_cselect_b32 s12, s20, s12
	s_xor_b32 s12, s12, s13
	s_sub_i32 s12, s12, s13
	s_add_i32 s18, s18, s12
	s_and_saveexec_b64 s[12:13], s[6:7]
	v_lshl_add_u32 v48, s18, 8, v4
	v_ashrrev_i32_e32 v49, 31, v48
	v_lshlrev_b64 v[48:49], 6, v[48:49]
	v_lshl_add_u64 v[24:25], s[8:9], 0, v[48:49]
	global_load_dwordx4 v[48:51], v[24:25], off
	global_load_dwordx4 v[52:55], v[24:25], off offset:16
	global_load_dwordx4 v[56:59], v[24:25], off offset:32
	global_load_dwordx4 v[60:63], v[24:25], off offset:48
	s_or_b64 exec, exec, s[12:13]
	s_add_u32 s10, s10, s54
	s_addc_u32 s11, s11, s55
	s_ashr_i32 s12, s10, 31
	s_lshr_b32 s12, s12, 29
	s_add_i32 s12, s10, s12
	s_ashr_i32 s13, s12, 3
	s_and_b32 s12, s12, -8
	s_sub_i32 s12, s10, s12
	s_cmp_lt_i32 s12, 0
	s_cselect_b32 s18, s16, 0xc0
	s_mul_i32 s12, s12, s18
	s_add_i32 s12, s12, s13
	s_mul_hi_i32 s13, s12, 0x2aaaaaab
	s_lshr_b32 s18, s13, 31
	s_ashr_i32 s13, s13, 2
	s_add_i32 s13, s13, s18
	s_lshl_b32 s18, s13, 1
	s_sub_i32 s19, 0x80, s18
	s_min_i32 s19, s19, 2
	s_abs_i32 s19, s19
	v_cvt_f32_u32_e32 v7, s19
	s_sub_i32 s20, 0, s19
	s_mul_i32 s13, s13, 24
	s_sub_i32 s12, s12, s13
	v_rcp_iflag_f32_e32 v7, v7
	s_ashr_i32 s13, s12, 31
	s_abs_i32 s12, s12
	v_mul_f32_e32 v7, 0x4f7ffffe, v7
	v_cvt_u32_f32_e32 v7, v7
	s_nop 0
	v_readfirstlane_b32 s21, v7
	s_mul_i32 s20, s20, s21
	s_mul_hi_u32 s20, s21, s20
	s_add_i32 s21, s21, s20
	s_mul_hi_u32 s20, s12, s21
	s_mul_i32 s20, s20, s19
	s_sub_i32 s12, s12, s20
	s_sub_i32 s20, s12, s19
	s_cmp_ge_u32 s12, s19
	s_cselect_b32 s12, s20, s12
	s_sub_i32 s20, s12, s19
	s_cmp_ge_u32 s12, s19
	s_cselect_b32 s12, s20, s12
	s_xor_b32 s12, s12, s13
	s_sub_i32 s12, s12, s13
	s_add_i32 s18, s18, s12
	s_and_saveexec_b64 s[12:13], s[6:7]
	v_lshl_add_u32 v64, s18, 8, v4
	v_ashrrev_i32_e32 v65, 31, v64
	v_lshlrev_b64 v[64:65], 6, v[64:65]
	v_lshl_add_u64 v[24:25], s[8:9], 0, v[64:65]
	global_load_dwordx4 v[64:67], v[24:25], off
	global_load_dwordx4 v[68:71], v[24:25], off offset:16
	global_load_dwordx4 v[72:75], v[24:25], off offset:32
	global_load_dwordx4 v[76:79], v[24:25], off offset:48
	s_or_b64 exec, exec, s[12:13]
	s_add_u32 s10, s10, s54
	s_addc_u32 s11, s11, s55
	s_ashr_i32 s12, s10, 31
	s_lshr_b32 s12, s12, 29
	s_add_i32 s12, s10, s12
	s_ashr_i32 s13, s12, 3
	s_and_b32 s12, s12, -8
	s_sub_i32 s12, s10, s12
	s_cmp_lt_i32 s12, 0
	s_cselect_b32 s18, s16, 0xc0
	s_mul_i32 s12, s12, s18
; #define LAS __attribute__((address_space(3)))
;     __device__ __forceinline__ bool next(int i, Unit& u) const {
;         const long L = (long)i * G + c; if (L >= nwg) return false;
;         int wgid = (int)L; { const int q = nwg / NXCD, r = nwg % NXCD, xcd = wgid % NXCD, off = wgid / NXCD; wgid = (xcd < r ? xcd * (q + 1) : r * (q + 1) + (xcd - r) * q) + off; }
;         const int nig = WGM * nN, gid = wgid / nig, fm = gid * WGM, gsz = (nM - fm) < WGM ? (nM - fm) : WGM;
;         u.pm = fm + ((wgid % nig) % gsz); u.pn = (wgid % nig) / gsz; u.idx = i; return true;
; __global__ void __launch_bounds__(512, 2) hybrid_fwd(Args args) {
;     ...
;         pg8::Gemm g{XB, WinO, 1024, 1024, 1024, 0, 128, 12}; pg8::StaticOrder S; S.init(128, 12, G, blk);
;         LAS float* rst = (LAS float*)(lds + 139264);
;         { pg8::Unit pu; for (int i = 0; S.next(i, pu); ++i) if (tid < 256) rst[i * 256 + tid] = row_rstd(SSQ + 2 * SSQ_STRIDE, pu.pm * 256 + tid);
;           __syncthreads(); }
	s_add_i32 s12, s12, s13
	s_mul_hi_i32 s13, s12, 0x2aaaaaab
	s_lshr_b32 s18, s13, 31
	s_ashr_i32 s13, s13, 2
	s_add_i32 s13, s13, s18
	s_lshl_b32 s18, s13, 1
	s_sub_i32 s19, 0x80, s18
	s_min_i32 s19, s19, 2
	s_abs_i32 s19, s19
	v_cvt_f32_u32_e32 v7, s19
	s_sub_i32 s20, 0, s19
	s_mul_i32 s13, s13, 24
	s_sub_i32 s12, s12, s13
	v_rcp_iflag_f32_e32 v7, v7
	s_ashr_i32 s13, s12, 31
	s_abs_i32 s12, s12
	v_mul_f32_e32 v7, 0x4f7ffffe, v7
	v_cvt_u32_f32_e32 v7, v7
	s_nop 0
	v_readfirstlane_b32 s21, v7
	s_mul_i32 s20, s20, s21
	s_mul_hi_u32 s20, s21, s20
	s_add_i32 s21, s21, s20
	s_mul_hi_u32 s20, s12, s21
	s_mul_i32 s20, s20, s19
	s_sub_i32 s12, s12, s20
	s_sub_i32 s20, s12, s19
	s_cmp_ge_u32 s12, s19
	s_cselect_b32 s12, s20, s12
	s_sub_i32 s20, s12, s19
	s_cmp_ge_u32 s12, s19
	s_cselect_b32 s12, s20, s12
	s_xor_b32 s12, s12, s13
	s_sub_i32 s12, s12, s13
	s_add_i32 s18, s18, s12
	s_and_saveexec_b64 s[12:13], s[6:7]
	v_lshl_add_u32 v80, s18, 8, v4
	v_ashrrev_i32_e32 v81, 31, v80
	v_lshlrev_b64 v[80:81], 6, v[80:81]
	v_lshl_add_u64 v[24:25], s[8:9], 0, v[80:81]
	global_load_dwordx4 v[80:83], v[24:25], off
	global_load_dwordx4 v[84:87], v[24:25], off offset:16
	global_load_dwordx4 v[88:91], v[24:25], off offset:32
	global_load_dwordx4 v[92:95], v[24:25], off offset:48
	s_or_b64 exec, exec, s[12:13]
	s_add_u32 s10, s10, s54
	s_addc_u32 s11, s11, s55
	s_ashr_i32 s12, s10, 31
	s_lshr_b32 s12, s12, 29
	s_add_i32 s12, s10, s12
	s_ashr_i32 s13, s12, 3
	s_and_b32 s12, s12, -8
	s_sub_i32 s12, s10, s12
	s_cmp_lt_i32 s12, 0
	s_cselect_b32 s18, s16, 0xc0
	s_mul_i32 s12, s12, s18
	s_add_i32 s12, s12, s13
	s_mul_hi_i32 s13, s12, 0x2aaaaaab
	s_lshr_b32 s18, s13, 31
	s_ashr_i32 s13, s13, 2
	s_add_i32 s13, s13, s18
	s_lshl_b32 s18, s13, 1
	s_sub_i32 s19, 0x80, s18
	s_min_i32 s19, s19, 2
	s_abs_i32 s19, s19
	v_cvt_f32_u32_e32 v7, s19
	s_sub_i32 s20, 0, s19
	s_mul_i32 s13, s13, 24
	s_sub_i32 s12, s12, s13
	v_rcp_iflag_f32_e32 v7, v7
	s_ashr_i32 s13, s12, 31
	s_abs_i32 s12, s12
	v_mul_f32_e32 v7, 0x4f7ffffe, v7
	v_cvt_u32_f32_e32 v7, v7
	s_nop 0
	v_readfirstlane_b32 s21, v7
	s_mul_i32 s20, s20, s21
	s_mul_hi_u32 s20, s21, s20
	s_add_i32 s21, s21, s20
	s_mul_hi_u32 s20, s12, s21
	s_mul_i32 s20, s20, s19
	s_sub_i32 s12, s12, s20
	s_sub_i32 s20, s12, s19
	s_cmp_ge_u32 s12, s19
	s_cselect_b32 s12, s20, s12
	s_sub_i32 s20, s12, s19
	s_cmp_ge_u32 s12, s19
	s_cselect_b32 s12, s20, s12
	s_xor_b32 s12, s12, s13
	s_sub_i32 s12, s12, s13
	s_add_i32 s18, s18, s12
	s_and_saveexec_b64 s[12:13], s[6:7]
	v_lshl_add_u32 v96, s18, 8, v4
	v_ashrrev_i32_e32 v97, 31, v96
	v_lshlrev_b64 v[96:97], 6, v[96:97]
	v_lshl_add_u64 v[24:25], s[8:9], 0, v[96:97]
	global_load_dwordx4 v[96:99], v[24:25], off
	global_load_dwordx4 v[100:103], v[24:25], off offset:16
	global_load_dwordx4 v[104:107], v[24:25], off offset:32
	global_load_dwordx4 v[108:111], v[24:25], off offset:48
	s_or_b64 exec, exec, s[12:13]
	s_add_u32 s10, s10, s54
	s_addc_u32 s11, s11, s55
	s_ashr_i32 s12, s10, 31
	s_lshr_b32 s12, s12, 29
	s_add_i32 s12, s10, s12
	s_ashr_i32 s13, s12, 3
	s_and_b32 s12, s12, -8
	s_sub_i32 s12, s10, s12
	s_cmp_lt_i32 s12, 0
	s_cselect_b32 s18, s16, 0xc0
	s_mul_i32 s12, s12, s18
	s_add_i32 s12, s12, s13
	s_mul_hi_i32 s13, s12, 0x2aaaaaab
	s_lshr_b32 s18, s13, 31
	s_ashr_i32 s13, s13, 2
	s_add_i32 s13, s13, s18
	s_lshl_b32 s18, s13, 1
	s_sub_i32 s19, 0x80, s18
	s_min_i32 s19, s19, 2
	s_abs_i32 s19, s19
	v_cvt_f32_u32_e32 v7, s19
	s_sub_i32 s20, 0, s19
	s_mul_i32 s13, s13, 24
	s_sub_i32 s12, s12, s13
	v_rcp_iflag_f32_e32 v7, v7
	s_ashr_i32 s13, s12, 31
	s_abs_i32 s12, s12
	v_mul_f32_e32 v7, 0x4f7ffffe, v7
	v_cvt_u32_f32_e32 v7, v7
	s_nop 0
	v_readfirstlane_b32 s21, v7
	s_mul_i32 s20, s20, s21
	s_mul_hi_u32 s20, s21, s20
	s_add_i32 s21, s21, s20
	s_mul_hi_u32 s20, s12, s21
	s_mul_i32 s20, s20, s19
	s_sub_i32 s12, s12, s20
	s_sub_i32 s20, s12, s19
	s_cmp_ge_u32 s12, s19
	s_cselect_b32 s12, s20, s12
	s_sub_i32 s20, s12, s19
	s_cmp_ge_u32 s12, s19
	s_cselect_b32 s12, s20, s12
	s_xor_b32 s12, s12, s13
	s_sub_i32 s12, s12, s13
	s_add_i32 s18, s18, s12
	s_and_saveexec_b64 s[12:13], s[6:7]
	v_lshl_add_u32 v112, s18, 8, v4
	v_ashrrev_i32_e32 v113, 31, v112
	v_lshlrev_b64 v[112:113], 6, v[112:113]
	v_lshl_add_u64 v[24:25], s[8:9], 0, v[112:113]
	global_load_dwordx4 v[112:115], v[24:25], off
	global_load_dwordx4 v[116:119], v[24:25], off offset:16
	global_load_dwordx4 v[120:123], v[24:25], off offset:32
	global_load_dwordx4 v[124:127], v[24:25], off offset:48
	s_or_b64 exec, exec, s[12:13]
	s_and_saveexec_b64 s[12:13], s[6:7]
	s_waitcnt vmcnt(0)
; __device__ __forceinline__ float row_rstd(const float* ssq, int row) {
;     const f32x4* p = (const f32x4*)(ssq + (size_t)row * 16);
;     const f32x4 a = p[0], b = p[1], c = p[2], d = p[3];
;     const float s = ((a[0] + a[1]) + (a[2] + a[3])) + ((b[0] + b[1]) + (b[2] + b[3])) + ((c[0] + c[1]) + (c[2] + c[3])) + ((d[0] + d[1]) + (d[2] + d[3]));
;     return rsqrtf(s * (1.0f / 1024.0f) + EPS);
; }
; __global__ void __launch_bounds__(512, 2) hybrid_fwd(Args args) {
;     ...
;         { pg8::Unit pu; for (int i = 0; S.next(i, pu); ++i) if (tid < 256) rst[i * 256 + tid] = row_rstd(SSQ + 2 * SSQ_STRIDE, pu.pm * 256 + tid);
	v_mov_b32_e32 v24, v33
	v_mov_b32_e32 v25, v34
	v_mov_b32_e32 v33, v35
	v_mov_b32_e32 v34, v37
	v_mov_b32_e32 v35, v38
	v_mov_b32_e32 v37, v39
	v_pk_add_f32 v[32:33], v[24:25], v[32:33]
	v_pk_add_f32 v[34:35], v[34:35], v[36:37]
	v_pk_add_f32 v[32:33], v[32:33], v[32:33] op_sel:[0,1] op_sel_hi:[1,0]
	v_pk_add_f32 v[34:35], v[34:35], v[34:35] op_sel:[0,1] op_sel_hi:[1,0]
	v_add_f32_e32 v38, v40, v41
	v_add_f32_e32 v40, v42, v43
	v_mov_b32_e32 v39, v46
	v_mov_b32_e32 v41, v47
	v_mov_b32_e32 v33, v44
	v_mov_b32_e32 v35, v45
	v_pk_add_f32 v[36:37], v[38:39], v[40:41]
	v_pk_add_f32 v[32:33], v[32:33], v[34:35]
	s_nop 0
	v_pk_add_f32 v[32:33], v[32:33], v[36:37]
	s_nop 0
	v_add_f32_e32 v7, v32, v33
	v_fmamk_f32 v7, v7, 0x3a800000, v6
	v_mul_f32_e32 v32, 0x4b800000, v7
	v_cmp_gt_f32_e32 vcc, s17, v7
	s_nop 1
	v_cndmask_b32_e32 v7, v7, v32, vcc
	v_rsq_f32_e32 v7, v7
	s_nop 0
	v_mul_f32_e32 v32, 0x45800000, v7
	v_cndmask_b32_e32 v7, v7, v32, vcc
	ds_write_b32 v5, v7
	v_mov_b32_e32 v24, v49
	v_mov_b32_e32 v25, v50
	v_mov_b32_e32 v49, v51
	v_mov_b32_e32 v50, v53
	v_mov_b32_e32 v51, v54
	v_mov_b32_e32 v53, v55
	v_pk_add_f32 v[48:49], v[24:25], v[48:49]
	v_pk_add_f32 v[50:51], v[50:51], v[52:53]
	v_pk_add_f32 v[48:49], v[48:49], v[48:49] op_sel:[0,1] op_sel_hi:[1,0]
	v_pk_add_f32 v[50:51], v[50:51], v[50:51] op_sel:[0,1] op_sel_hi:[1,0]
	v_add_f32_e32 v54, v56, v57
	v_add_f32_e32 v56, v58, v59
	v_mov_b32_e32 v55, v62
	v_mov_b32_e32 v57, v63
	v_mov_b32_e32 v49, v60
	v_mov_b32_e32 v51, v61
	v_pk_add_f32 v[52:53], v[54:55], v[56:57]
	v_pk_add_f32 v[48:49], v[48:49], v[50:51]
	s_nop 0
	v_pk_add_f32 v[48:49], v[48:49], v[52:53]
	s_nop 0
	v_add_f32_e32 v7, v48, v49
	v_fmamk_f32 v7, v7, 0x3a800000, v6
	v_mul_f32_e32 v48, 0x4b800000, v7
	v_cmp_gt_f32_e32 vcc, s17, v7
	s_nop 1
	v_cndmask_b32_e32 v7, v7, v48, vcc
	v_rsq_f32_e32 v7, v7
	s_nop 0
	v_mul_f32_e32 v48, 0x45800000, v7
	v_cndmask_b32_e32 v7, v7, v48, vcc
	ds_write_b32 v5, v7 offset:1024
	v_mov_b32_e32 v24, v65
	v_mov_b32_e32 v25, v66
	v_mov_b32_e32 v65, v67
	v_mov_b32_e32 v66, v69
	v_mov_b32_e32 v67, v70
	v_mov_b32_e32 v69, v71
	v_pk_add_f32 v[64:65], v[24:25], v[64:65]
	v_pk_add_f32 v[66:67], v[66:67], v[68:69]
	v_pk_add_f32 v[64:65], v[64:65], v[64:65] op_sel:[0,1] op_sel_hi:[1,0]
	v_pk_add_f32 v[66:67], v[66:67], v[66:67] op_sel:[0,1] op_sel_hi:[1,0]
	v_add_f32_e32 v70, v72, v73
	v_add_f32_e32 v72, v74, v75
	v_mov_b32_e32 v71, v78
	v_mov_b32_e32 v73, v79
	v_mov_b32_e32 v65, v76
	v_mov_b32_e32 v67, v77
	v_pk_add_f32 v[68:69], v[70:71], v[72:73]
	v_pk_add_f32 v[64:65], v[64:65], v[66:67]
	s_nop 0
	v_pk_add_f32 v[64:65], v[64:65], v[68:69]
	s_nop 0
	v_add_f32_e32 v7, v64, v65
	v_fmamk_f32 v7, v7, 0x3a800000, v6
	v_mul_f32_e32 v64, 0x4b800000, v7
	v_cmp_gt_f32_e32 vcc, s17, v7
	s_nop 1
	v_cndmask_b32_e32 v7, v7, v64, vcc
	v_rsq_f32_e32 v7, v7
	s_nop 0
	v_mul_f32_e32 v64, 0x45800000, v7
	v_cndmask_b32_e32 v7, v7, v64, vcc
	ds_write_b32 v5, v7 offset:2048
	v_mov_b32_e32 v24, v81
	v_mov_b32_e32 v25, v82
	v_mov_b32_e32 v81, v83
	v_mov_b32_e32 v82, v85
	v_mov_b32_e32 v83, v86
	v_mov_b32_e32 v85, v87
	v_pk_add_f32 v[80:81], v[24:25], v[80:81]
	v_pk_add_f32 v[82:83], v[82:83], v[84:85]
	v_pk_add_f32 v[80:81], v[80:81], v[80:81] op_sel:[0,1] op_sel_hi:[1,0]
	v_pk_add_f32 v[82:83], v[82:83], v[82:83] op_sel:[0,1] op_sel_hi:[1,0]
	v_add_f32_e32 v86, v88, v89
	v_add_f32_e32 v88, v90, v91
	v_mov_b32_e32 v87, v94
	v_mov_b32_e32 v89, v95
	v_mov_b32_e32 v81, v92
	v_mov_b32_e32 v83, v93
	v_pk_add_f32 v[84:85], v[86:87], v[88:89]
	v_pk_add_f32 v[80:81], v[80:81], v[82:83]
	s_nop 0
	v_pk_add_f32 v[80:81], v[80:81], v[84:85]
	s_nop 0
	v_add_f32_e32 v7, v80, v81
	v_fmamk_f32 v7, v7, 0x3a800000, v6
	v_mul_f32_e32 v80, 0x4b800000, v7
	v_cmp_gt_f32_e32 vcc, s17, v7
	s_nop 1
	v_cndmask_b32_e32 v7, v7, v80, vcc
	v_rsq_f32_e32 v7, v7
	s_nop 0
	v_mul_f32_e32 v80, 0x45800000, v7
	v_cndmask_b32_e32 v7, v7, v80, vcc
	ds_write_b32 v5, v7 offset:3072
	v_mov_b32_e32 v24, v97
	v_mov_b32_e32 v25, v98
	v_mov_b32_e32 v97, v99
	v_mov_b32_e32 v98, v101
	v_mov_b32_e32 v99, v102
	v_mov_b32_e32 v101, v103
	v_pk_add_f32 v[96:97], v[24:25], v[96:97]
	v_pk_add_f32 v[98:99], v[98:99], v[100:101]
	v_pk_add_f32 v[96:97], v[96:97], v[96:97] op_sel:[0,1] op_sel_hi:[1,0]
	v_pk_add_f32 v[98:99], v[98:99], v[98:99] op_sel:[0,1] op_sel_hi:[1,0]
	v_add_f32_e32 v102, v104, v105
	v_add_f32_e32 v104, v106, v107
	v_mov_b32_e32 v103, v110
	v_mov_b32_e32 v105, v111
	v_mov_b32_e32 v97, v108
	v_mov_b32_e32 v99, v109
	v_pk_add_f32 v[100:101], v[102:103], v[104:105]
	v_pk_add_f32 v[96:97], v[96:97], v[98:99]
	s_nop 0
	v_pk_add_f32 v[96:97], v[96:97], v[100:101]
	s_nop 0
	v_add_f32_e32 v7, v96, v97
	v_fmamk_f32 v7, v7, 0x3a800000, v6
	v_mul_f32_e32 v96, 0x4b800000, v7
	v_cmp_gt_f32_e32 vcc, s17, v7
	s_nop 1
	v_cndmask_b32_e32 v7, v7, v96, vcc
	v_rsq_f32_e32 v7, v7
	s_nop 0
	v_mul_f32_e32 v96, 0x45800000, v7
	v_cndmask_b32_e32 v7, v7, v96, vcc
	ds_write_b32 v5, v7 offset:4096
	v_mov_b32_e32 v24, v113
	v_mov_b32_e32 v25, v114
	v_mov_b32_e32 v113, v115
	v_mov_b32_e32 v114, v117
	v_mov_b32_e32 v115, v118
	v_mov_b32_e32 v117, v119
	v_pk_add_f32 v[112:113], v[24:25], v[112:113]
	v_pk_add_f32 v[114:115], v[114:115], v[116:117]
	v_pk_add_f32 v[112:113], v[112:113], v[112:113] op_sel:[0,1] op_sel_hi:[1,0]
	v_pk_add_f32 v[114:115], v[114:115], v[114:115] op_sel:[0,1] op_sel_hi:[1,0]
	v_add_f32_e32 v118, v120, v121
	v_add_f32_e32 v120, v122, v123
	v_mov_b32_e32 v119, v126
	v_mov_b32_e32 v121, v127
	v_mov_b32_e32 v113, v124
	v_mov_b32_e32 v115, v125
	v_pk_add_f32 v[116:117], v[118:119], v[120:121]
	v_pk_add_f32 v[112:113], v[112:113], v[114:115]
	s_nop 0
	v_pk_add_f32 v[112:113], v[112:113], v[116:117]
	s_nop 0
	v_add_f32_e32 v7, v112, v113
	v_fmamk_f32 v7, v7, 0x3a800000, v6
	v_mul_f32_e32 v112, 0x4b800000, v7
	v_cmp_gt_f32_e32 vcc, s17, v7
	s_nop 1
	v_cndmask_b32_e32 v7, v7, v112, vcc
	v_rsq_f32_e32 v7, v7
	s_nop 0
	v_mul_f32_e32 v112, 0x45800000, v7
	v_cndmask_b32_e32 v7, v7, v112, vcc
	ds_write_b32 v5, v7 offset:5120
	s_or_b64 exec, exec, s[12:13]
	s_branch .LBB0_813

; #define LAS __attribute__((address_space(3)))
;     __device__ __forceinline__ bool next(int i, Unit& u) const {
;         const long L = (long)i * G + c; if (L >= nwg) return false;
;         int wgid = (int)L; { const int q = nwg / NXCD, r = nwg % NXCD, xcd = wgid % NXCD, off = wgid / NXCD; wgid = (xcd < r ? xcd * (q + 1) : r * (q + 1) + (xcd - r) * q) + off; }
;         const int nig = WGM * nN, gid = wgid / nig, fm = gid * WGM, gsz = (nM - fm) < WGM ? (nM - fm) : WGM;
;         u.pm = fm + ((wgid % nig) % gsz); u.pn = (wgid % nig) / gsz; u.idx = i; return true;
; __global__ void __launch_bounds__(512, 2) hybrid_fwd(Args args) {
;     ...
;         pg8::Gemm g{XB, Wup + (size_t)FF2 * 1024, 1024, 1024, 1024, 0, 128, 22}; pg8::StaticOrder S; S.init(128, 22, G, blk);
;         LAS float* rst = (LAS float*)(lds + 139264);
;         { pg8::Unit pu; for (int i = 0; S.next(i, pu); ++i) if (tid < 256) rst[i * 256 + tid] = row_rstd(SSQ + 3 * SSQ_STRIDE, pu.pm * 256 + tid);
;           __syncthreads(); }
.LBB0_1258:
	s_cmp_lt_i32 s82, 13
	s_cselect_b64 s[8:9], -1, 0
	s_and_b64 s[18:19], s[8:9], s[6:7]
	s_andn2_b64 vcc, exec, s[18:19]
	s_cbranch_vccnz .LBB0_1318
	v_mov_b32_e32 v4, v220
	s_load_dword s46, s[0:1], 0xb0
	s_waitcnt lgkmcnt(0)
	s_ashr_i32 s3, s2, 31
	s_movk_i32 s6, 0x100
	v_lshl_add_u32 v0, v4, 2, 0
	v_cmp_gt_i32_e64 s[6:7], s6, v4
	s_ashr_i32 s47, s46, 31
	s_add_u32 s8, s80, 0x3a00000
	s_addc_u32 s9, s81, 0
	v_add_u32_e32 v5, 0x22000, v0
	v_mov_b64_e32 v[0:1], 0xb00
	v_mov_b64_e32 v[2:3], 0xaff
	s_movk_i32 s14, 0x161
	v_mov_b32_e32 v6, 0x358637bd
	s_mov_b32 s15, 0x800000
	s_mov_b64 s[10:11], s[2:3]
	s_cmp_lg_u32 s46, 0x100
	s_cbranch_scc1 .Lrs3_slow
	s_ashr_i32 s12, s10, 31
	s_lshr_b32 s12, s12, 29
	s_add_i32 s12, s10, s12
	s_ashr_i32 s13, s12, 3
	s_and_b32 s12, s12, -8
	s_sub_i32 s12, s10, s12
	s_cmp_lt_i32 s12, 0
	s_cselect_b32 s16, s14, 0x160
	s_mul_i32 s12, s12, s16
	s_add_i32 s12, s12, s13
	s_mul_hi_i32 s13, s12, 0x2e8ba2e9
	s_lshr_b32 s16, s13, 31
	s_ashr_i32 s13, s13, 3
	s_add_i32 s13, s13, s16
	s_lshl_b32 s16, s13, 1
	s_sub_i32 s17, 0x80, s16
	s_min_i32 s17, s17, 2
	s_abs_i32 s17, s17
	v_cvt_f32_u32_e32 v7, s17
	s_sub_i32 s20, 0, s17
	s_mul_i32 s13, s13, 44
	s_sub_i32 s12, s12, s13
	v_rcp_iflag_f32_e32 v7, v7
	s_ashr_i32 s13, s12, 31
	s_abs_i32 s12, s12
	v_mul_f32_e32 v7, 0x4f7ffffe, v7
	v_cvt_u32_f32_e32 v7, v7
	s_nop 0
	v_readfirstlane_b32 s21, v7
	s_mul_i32 s20, s20, s21
	s_mul_hi_u32 s20, s21, s20
	s_add_i32 s21, s21, s20
	s_mul_hi_u32 s20, s12, s21
	s_mul_i32 s20, s20, s17
	s_sub_i32 s12, s12, s20
	s_sub_i32 s20, s12, s17
	s_cmp_ge_u32 s12, s17
	s_cselect_b32 s12, s20, s12
	s_sub_i32 s20, s12, s17
	s_cmp_ge_u32 s12, s17
	s_cselect_b32 s12, s20, s12
	s_xor_b32 s12, s12, s13
	s_sub_i32 s12, s12, s13
	s_add_i32 s16, s16, s12
	s_and_saveexec_b64 s[12:13], s[6:7]
	v_lshl_add_u32 v32, s16, 8, v4
	v_ashrrev_i32_e32 v33, 31, v32
	v_lshlrev_b64 v[32:33], 6, v[32:33]
	v_lshl_add_u64 v[24:25], s[8:9], 0, v[32:33]
	global_load_dwordx4 v[32:35], v[24:25], off
	global_load_dwordx4 v[36:39], v[24:25], off offset:16
	global_load_dwordx4 v[40:43], v[24:25], off offset:32
	global_load_dwordx4 v[44:47], v[24:25], off offset:48
	s_or_b64 exec, exec, s[12:13]
	s_add_u32 s10, s10, s46
	s_addc_u32 s11, s11, s47
	s_ashr_i32 s12, s10, 31
	s_lshr_b32 s12, s12, 29
	s_add_i32 s12, s10, s12
	s_ashr_i32 s13, s12, 3
	s_and_b32 s12, s12, -8
	s_sub_i32 s12, s10, s12
	s_cmp_lt_i32 s12, 0
	s_cselect_b32 s16, s14, 0x160
	s_mul_i32 s12, s12, s16
	s_add_i32 s12, s12, s13
	s_mul_hi_i32 s13, s12, 0x2e8ba2e9
	s_lshr_b32 s16, s13, 31
	s_ashr_i32 s13, s13, 3
	s_add_i32 s13, s13, s16
	s_lshl_b32 s16, s13, 1
	s_sub_i32 s17, 0x80, s16
	s_min_i32 s17, s17, 2
	s_abs_i32 s17, s17
	v_cvt_f32_u32_e32 v7, s17
	s_sub_i32 s20, 0, s17
	s_mul_i32 s13, s13, 44
	s_sub_i32 s12, s12, s13
	v_rcp_iflag_f32_e32 v7, v7
	s_ashr_i32 s13, s12, 31
	s_abs_i32 s12, s12
	v_mul_f32_e32 v7, 0x4f7ffffe, v7
	v_cvt_u32_f32_e32 v7, v7
	s_nop 0
	v_readfirstlane_b32 s21, v7
	s_mul_i32 s20, s20, s21
	s_mul_hi_u32 s20, s21, s20
	s_add_i32 s21, s21, s20
	s_mul_hi_u32 s20, s12, s21
	s_mul_i32 s20, s20, s17
	s_sub_i32 s12, s12, s20
	s_sub_i32 s20, s12, s17
	s_cmp_ge_u32 s12, s17
	s_cselect_b32 s12, s20, s12
	s_sub_i32 s20, s12, s17
	s_cmp_ge_u32 s12, s17
	s_cselect_b32 s12, s20, s12
	s_xor_b32 s12, s12, s13
	s_sub_i32 s12, s12, s13
	s_add_i32 s16, s16, s12
	s_and_saveexec_b64 s[12:13], s[6:7]
	v_lshl_add_u32 v48, s16, 8, v4
	v_ashrrev_i32_e32 v49, 31, v48
	v_lshlrev_b64 v[48:49], 6, v[48:49]
	v_lshl_add_u64 v[24:25], s[8:9], 0, v[48:49]
	global_load_dwordx4 v[48:51], v[24:25], off
	global_load_dwordx4 v[52:55], v[24:25], off offset:16
	global_load_dwordx4 v[56:59], v[24:25], off offset:32
	global_load_dwordx4 v[60:63], v[24:25], off offset:48
	s_or_b64 exec, exec, s[12:13]
	s_add_u32 s10, s10, s46
	s_addc_u32 s11, s11, s47
	s_ashr_i32 s12, s10, 31
	s_lshr_b32 s12, s12, 29
	s_add_i32 s12, s10, s12
	s_ashr_i32 s13, s12, 3
	s_and_b32 s12, s12, -8
	s_sub_i32 s12, s10, s12
	s_cmp_lt_i32 s12, 0
	s_cselect_b32 s16, s14, 0x160
	s_mul_i32 s12, s12, s16
	s_add_i32 s12, s12, s13
	s_mul_hi_i32 s13, s12, 0x2e8ba2e9
	s_lshr_b32 s16, s13, 31
	s_ashr_i32 s13, s13, 3
	s_add_i32 s13, s13, s16
	s_lshl_b32 s16, s13, 1
	s_sub_i32 s17, 0x80, s16
	s_min_i32 s17, s17, 2
	s_abs_i32 s17, s17
	v_cvt_f32_u32_e32 v7, s17
	s_sub_i32 s20, 0, s17
	s_mul_i32 s13, s13, 44
	s_sub_i32 s12, s12, s13
	v_rcp_iflag_f32_e32 v7, v7
	s_ashr_i32 s13, s12, 31
	s_abs_i32 s12, s12
	v_mul_f32_e32 v7, 0x4f7ffffe, v7
	v_cvt_u32_f32_e32 v7, v7
	s_nop 0
	v_readfirstlane_b32 s21, v7
	s_mul_i32 s20, s20, s21
	s_mul_hi_u32 s20, s21, s20
	s_add_i32 s21, s21, s20
	s_mul_hi_u32 s20, s12, s21
	s_mul_i32 s20, s20, s17
	s_sub_i32 s12, s12, s20
	s_sub_i32 s20, s12, s17
	s_cmp_ge_u32 s12, s17
	s_cselect_b32 s12, s20, s12
	s_sub_i32 s20, s12, s17
	s_cmp_ge_u32 s12, s17
	s_cselect_b32 s12, s20, s12
	s_xor_b32 s12, s12, s13
	s_sub_i32 s12, s12, s13
	s_add_i32 s16, s16, s12
	s_and_saveexec_b64 s[12:13], s[6:7]
	v_lshl_add_u32 v64, s16, 8, v4
	v_ashrrev_i32_e32 v65, 31, v64
	v_lshlrev_b64 v[64:65], 6, v[64:65]
	v_lshl_add_u64 v[24:25], s[8:9], 0, v[64:65]
	global_load_dwordx4 v[64:67], v[24:25], off
	global_load_dwordx4 v[68:71], v[24:25], off offset:16
	global_load_dwordx4 v[72:75], v[24:25], off offset:32
	global_load_dwordx4 v[76:79], v[24:25], off offset:48
	s_or_b64 exec, exec, s[12:13]
	s_add_u32 s10, s10, s46
	s_addc_u32 s11, s11, s47
	s_ashr_i32 s12, s10, 31
	s_lshr_b32 s12, s12, 29
	s_add_i32 s12, s10, s12
	s_ashr_i32 s13, s12, 3
	s_and_b32 s12, s12, -8
	s_sub_i32 s12, s10, s12
	s_cmp_lt_i32 s12, 0
	s_cselect_b32 s16, s14, 0x160
	s_mul_i32 s12, s12, s16
; #define LAS __attribute__((address_space(3)))
;     __device__ __forceinline__ bool next(int i, Unit& u) const {
;         const long L = (long)i * G + c; if (L >= nwg) return false;
;         int wgid = (int)L; { const int q = nwg / NXCD, r = nwg % NXCD, xcd = wgid % NXCD, off = wgid / NXCD; wgid = (xcd < r ? xcd * (q + 1) : r * (q + 1) + (xcd - r) * q) + off; }
;         const int nig = WGM * nN, gid = wgid / nig, fm = gid * WGM, gsz = (nM - fm) < WGM ? (nM - fm) : WGM;
;         u.pm = fm + ((wgid % nig) % gsz); u.pn = (wgid % nig) / gsz; u.idx = i; return true;
; __global__ void __launch_bounds__(512, 2) hybrid_fwd(Args args) {
;     ...
;         pg8::Gemm g{XB, Wup + (size_t)FF2 * 1024, 1024, 1024, 1024, 0, 128, 22}; pg8::StaticOrder S; S.init(128, 22, G, blk);
;         LAS float* rst = (LAS float*)(lds + 139264);
;         { pg8::Unit pu; for (int i = 0; S.next(i, pu); ++i) if (tid < 256) rst[i * 256 + tid] = row_rstd(SSQ + 3 * SSQ_STRIDE, pu.pm * 256 + tid);
;           __syncthreads(); }
	s_add_i32 s12, s12, s13
	s_mul_hi_i32 s13, s12, 0x2e8ba2e9
	s_lshr_b32 s16, s13, 31
	s_ashr_i32 s13, s13, 3
	s_add_i32 s13, s13, s16
	s_lshl_b32 s16, s13, 1
	s_sub_i32 s17, 0x80, s16
	s_min_i32 s17, s17, 2
	s_abs_i32 s17, s17
	v_cvt_f32_u32_e32 v7, s17
	s_sub_i32 s20, 0, s17
	s_mul_i32 s13, s13, 44
	s_sub_i32 s12, s12, s13
	v_rcp_iflag_f32_e32 v7, v7
	s_ashr_i32 s13, s12, 31
	s_abs_i32 s12, s12
	v_mul_f32_e32 v7, 0x4f7ffffe, v7
	v_cvt_u32_f32_e32 v7, v7
	s_nop 0
	v_readfirstlane_b32 s21, v7
	s_mul_i32 s20, s20, s21
	s_mul_hi_u32 s20, s21, s20
	s_add_i32 s21, s21, s20
	s_mul_hi_u32 s20, s12, s21
	s_mul_i32 s20, s20, s17
	s_sub_i32 s12, s12, s20
	s_sub_i32 s20, s12, s17
	s_cmp_ge_u32 s12, s17
	s_cselect_b32 s12, s20, s12
	s_sub_i32 s20, s12, s17
	s_cmp_ge_u32 s12, s17
	s_cselect_b32 s12, s20, s12
	s_xor_b32 s12, s12, s13
	s_sub_i32 s12, s12, s13
	s_add_i32 s16, s16, s12
	s_and_saveexec_b64 s[12:13], s[6:7]
	v_lshl_add_u32 v80, s16, 8, v4
	v_ashrrev_i32_e32 v81, 31, v80
	v_lshlrev_b64 v[80:81], 6, v[80:81]
	v_lshl_add_u64 v[24:25], s[8:9], 0, v[80:81]
	global_load_dwordx4 v[80:83], v[24:25], off
	global_load_dwordx4 v[84:87], v[24:25], off offset:16
	global_load_dwordx4 v[88:91], v[24:25], off offset:32
	global_load_dwordx4 v[92:95], v[24:25], off offset:48
	s_or_b64 exec, exec, s[12:13]
	s_add_u32 s10, s10, s46
	s_addc_u32 s11, s11, s47
	s_ashr_i32 s12, s10, 31
	s_lshr_b32 s12, s12, 29
	s_add_i32 s12, s10, s12
	s_ashr_i32 s13, s12, 3
	s_and_b32 s12, s12, -8
	s_sub_i32 s12, s10, s12
	s_cmp_lt_i32 s12, 0
	s_cselect_b32 s16, s14, 0x160
	s_mul_i32 s12, s12, s16
	s_add_i32 s12, s12, s13
	s_mul_hi_i32 s13, s12, 0x2e8ba2e9
	s_lshr_b32 s16, s13, 31
	s_ashr_i32 s13, s13, 3
	s_add_i32 s13, s13, s16
	s_lshl_b32 s16, s13, 1
	s_sub_i32 s17, 0x80, s16
	s_min_i32 s17, s17, 2
	s_abs_i32 s17, s17
	v_cvt_f32_u32_e32 v7, s17
	s_sub_i32 s20, 0, s17
	s_mul_i32 s13, s13, 44
	s_sub_i32 s12, s12, s13
	v_rcp_iflag_f32_e32 v7, v7
	s_ashr_i32 s13, s12, 31
	s_abs_i32 s12, s12
	v_mul_f32_e32 v7, 0x4f7ffffe, v7
	v_cvt_u32_f32_e32 v7, v7
	s_nop 0
	v_readfirstlane_b32 s21, v7
	s_mul_i32 s20, s20, s21
	s_mul_hi_u32 s20, s21, s20
	s_add_i32 s21, s21, s20
	s_mul_hi_u32 s20, s12, s21
	s_mul_i32 s20, s20, s17
	s_sub_i32 s12, s12, s20
	s_sub_i32 s20, s12, s17
	s_cmp_ge_u32 s12, s17
	s_cselect_b32 s12, s20, s12
	s_sub_i32 s20, s12, s17
	s_cmp_ge_u32 s12, s17
	s_cselect_b32 s12, s20, s12
	s_xor_b32 s12, s12, s13
	s_sub_i32 s12, s12, s13
	s_add_i32 s16, s16, s12
	s_and_saveexec_b64 s[12:13], s[6:7]
	v_lshl_add_u32 v96, s16, 8, v4
	v_ashrrev_i32_e32 v97, 31, v96
	v_lshlrev_b64 v[96:97], 6, v[96:97]
	v_lshl_add_u64 v[24:25], s[8:9], 0, v[96:97]
	global_load_dwordx4 v[96:99], v[24:25], off
	global_load_dwordx4 v[100:103], v[24:25], off offset:16
	global_load_dwordx4 v[104:107], v[24:25], off offset:32
	global_load_dwordx4 v[108:111], v[24:25], off offset:48
	s_or_b64 exec, exec, s[12:13]
	s_add_u32 s10, s10, s46
	s_addc_u32 s11, s11, s47
	s_ashr_i32 s12, s10, 31
	s_lshr_b32 s12, s12, 29
	s_add_i32 s12, s10, s12
	s_ashr_i32 s13, s12, 3
	s_and_b32 s12, s12, -8
	s_sub_i32 s12, s10, s12
	s_cmp_lt_i32 s12, 0
	s_cselect_b32 s16, s14, 0x160
	s_mul_i32 s12, s12, s16
	s_add_i32 s12, s12, s13
	s_mul_hi_i32 s13, s12, 0x2e8ba2e9
	s_lshr_b32 s16, s13, 31
	s_ashr_i32 s13, s13, 3
	s_add_i32 s13, s13, s16
	s_lshl_b32 s16, s13, 1
	s_sub_i32 s17, 0x80, s16
	s_min_i32 s17, s17, 2
	s_abs_i32 s17, s17
	v_cvt_f32_u32_e32 v7, s17
	s_sub_i32 s20, 0, s17
	s_mul_i32 s13, s13, 44
	s_sub_i32 s12, s12, s13
	v_rcp_iflag_f32_e32 v7, v7
	s_ashr_i32 s13, s12, 31
	s_abs_i32 s12, s12
	v_mul_f32_e32 v7, 0x4f7ffffe, v7
	v_cvt_u32_f32_e32 v7, v7
	s_nop 0
	v_readfirstlane_b32 s21, v7
	s_mul_i32 s20, s20, s21
	s_mul_hi_u32 s20, s21, s20
	s_add_i32 s21, s21, s20
	s_mul_hi_u32 s20, s12, s21
	s_mul_i32 s20, s20, s17
	s_sub_i32 s12, s12, s20
	s_sub_i32 s20, s12, s17
	s_cmp_ge_u32 s12, s17
	s_cselect_b32 s12, s20, s12
	s_sub_i32 s20, s12, s17
	s_cmp_ge_u32 s12, s17
	s_cselect_b32 s12, s20, s12
	s_xor_b32 s12, s12, s13
	s_sub_i32 s12, s12, s13
	s_add_i32 s16, s16, s12
	s_and_saveexec_b64 s[12:13], s[6:7]
	v_lshl_add_u32 v112, s16, 8, v4
	v_ashrrev_i32_e32 v113, 31, v112
	v_lshlrev_b64 v[112:113], 6, v[112:113]
	v_lshl_add_u64 v[24:25], s[8:9], 0, v[112:113]
	global_load_dwordx4 v[112:115], v[24:25], off
	global_load_dwordx4 v[116:119], v[24:25], off offset:16
	global_load_dwordx4 v[120:123], v[24:25], off offset:32
	global_load_dwordx4 v[124:127], v[24:25], off offset:48
	s_or_b64 exec, exec, s[12:13]
	s_add_u32 s10, s10, s46
	s_addc_u32 s11, s11, s47
	s_ashr_i32 s12, s10, 31
	s_lshr_b32 s12, s12, 29
	s_add_i32 s12, s10, s12
	s_ashr_i32 s13, s12, 3
	s_and_b32 s12, s12, -8
	s_sub_i32 s12, s10, s12
	s_cmp_lt_i32 s12, 0
	s_cselect_b32 s16, s14, 0x160
	s_mul_i32 s12, s12, s16
	s_add_i32 s12, s12, s13
	s_mul_hi_i32 s13, s12, 0x2e8ba2e9
	s_lshr_b32 s16, s13, 31
	s_ashr_i32 s13, s13, 3
	s_add_i32 s13, s13, s16
	s_lshl_b32 s16, s13, 1
	s_sub_i32 s17, 0x80, s16
	s_min_i32 s17, s17, 2
	s_abs_i32 s17, s17
	v_cvt_f32_u32_e32 v7, s17
	s_sub_i32 s20, 0, s17
	s_mul_i32 s13, s13, 44
	s_sub_i32 s12, s12, s13
	v_rcp_iflag_f32_e32 v7, v7
	s_ashr_i32 s13, s12, 31
	s_abs_i32 s12, s12
	v_mul_f32_e32 v7, 0x4f7ffffe, v7
	v_cvt_u32_f32_e32 v7, v7
	s_nop 0
	v_readfirstlane_b32 s21, v7
	s_mul_i32 s20, s20, s21
	s_mul_hi_u32 s20, s21, s20
	s_add_i32 s21, s21, s20
	s_mul_hi_u32 s20, s12, s21
	s_mul_i32 s20, s20, s17
	s_sub_i32 s12, s12, s20
	s_sub_i32 s20, s12, s17
	s_cmp_ge_u32 s12, s17
	s_cselect_b32 s12, s20, s12
	s_sub_i32 s20, s12, s17
	s_cmp_ge_u32 s12, s17
	s_cselect_b32 s12, s20, s12
	s_xor_b32 s12, s12, s13
	s_sub_i32 s12, s12, s13
; #define LAS __attribute__((address_space(3)))
;     __device__ __forceinline__ bool next(int i, Unit& u) const {
;         const long L = (long)i * G + c; if (L >= nwg) return false;
;         int wgid = (int)L; { const int q = nwg / NXCD, r = nwg % NXCD, xcd = wgid % NXCD, off = wgid / NXCD; wgid = (xcd < r ? xcd * (q + 1) : r * (q + 1) + (xcd - r) * q) + off; }
;         const int nig = WGM * nN, gid = wgid / nig, fm = gid * WGM, gsz = (nM - fm) < WGM ? (nM - fm) : WGM;
;         u.pm = fm + ((wgid % nig) % gsz); u.pn = (wgid % nig) / gsz; u.idx = i; return true;
; __global__ void __launch_bounds__(512, 2) hybrid_fwd(Args args) {
;     ...
;         pg8::Gemm g{XB, Wup + (size_t)FF2 * 1024, 1024, 1024, 1024, 0, 128, 22}; pg8::StaticOrder S; S.init(128, 22, G, blk);
;         LAS float* rst = (LAS float*)(lds + 139264);
;         { pg8::Unit pu; for (int i = 0; S.next(i, pu); ++i) if (tid < 256) rst[i * 256 + tid] = row_rstd(SSQ + 3 * SSQ_STRIDE, pu.pm * 256 + tid);
;           __syncthreads(); }
	s_add_i32 s16, s16, s12
	s_and_saveexec_b64 s[12:13], s[6:7]
	v_lshl_add_u32 v128, s16, 8, v4
	v_ashrrev_i32_e32 v129, 31, v128
	v_lshlrev_b64 v[128:129], 6, v[128:129]
	v_lshl_add_u64 v[24:25], s[8:9], 0, v[128:129]
	global_load_dwordx4 v[128:131], v[24:25], off
	global_load_dwordx4 v[132:135], v[24:25], off offset:16
	global_load_dwordx4 v[136:139], v[24:25], off offset:32
	global_load_dwordx4 v[140:143], v[24:25], off offset:48
	s_or_b64 exec, exec, s[12:13]
	s_add_u32 s10, s10, s46
	s_addc_u32 s11, s11, s47
	s_ashr_i32 s12, s10, 31
	s_lshr_b32 s12, s12, 29
	s_add_i32 s12, s10, s12
	s_ashr_i32 s13, s12, 3
	s_and_b32 s12, s12, -8
	s_sub_i32 s12, s10, s12
	s_cmp_lt_i32 s12, 0
	s_cselect_b32 s16, s14, 0x160
	s_mul_i32 s12, s12, s16
	s_add_i32 s12, s12, s13
	s_mul_hi_i32 s13, s12, 0x2e8ba2e9
	s_lshr_b32 s16, s13, 31
	s_ashr_i32 s13, s13, 3
	s_add_i32 s13, s13, s16
	s_lshl_b32 s16, s13, 1
	s_sub_i32 s17, 0x80, s16
	s_min_i32 s17, s17, 2
	s_abs_i32 s17, s17
	v_cvt_f32_u32_e32 v7, s17
	s_sub_i32 s20, 0, s17
	s_mul_i32 s13, s13, 44
	s_sub_i32 s12, s12, s13
	v_rcp_iflag_f32_e32 v7, v7
	s_ashr_i32 s13, s12, 31
	s_abs_i32 s12, s12
	v_mul_f32_e32 v7, 0x4f7ffffe, v7
	v_cvt_u32_f32_e32 v7, v7
	s_nop 0
	v_readfirstlane_b32 s21, v7
	s_mul_i32 s20, s20, s21
	s_mul_hi_u32 s20, s21, s20
	s_add_i32 s21, s21, s20
	s_mul_hi_u32 s20, s12, s21
	s_mul_i32 s20, s20, s17
	s_sub_i32 s12, s12, s20
	s_sub_i32 s20, s12, s17
	s_cmp_ge_u32 s12, s17
	s_cselect_b32 s12, s20, s12
	s_sub_i32 s20, s12, s17
	s_cmp_ge_u32 s12, s17
	s_cselect_b32 s12, s20, s12
	s_xor_b32 s12, s12, s13
	s_sub_i32 s12, s12, s13
	s_add_i32 s16, s16, s12
	s_and_saveexec_b64 s[12:13], s[6:7]
	v_lshl_add_u32 v144, s16, 8, v4
	v_ashrrev_i32_e32 v145, 31, v144
	v_lshlrev_b64 v[144:145], 6, v[144:145]
	v_lshl_add_u64 v[24:25], s[8:9], 0, v[144:145]
	global_load_dwordx4 v[144:147], v[24:25], off
	global_load_dwordx4 v[148:151], v[24:25], off offset:16
	global_load_dwordx4 v[152:155], v[24:25], off offset:32
	global_load_dwordx4 v[156:159], v[24:25], off offset:48
	s_or_b64 exec, exec, s[12:13]
	s_add_u32 s10, s10, s46
	s_addc_u32 s11, s11, s47
	s_ashr_i32 s12, s10, 31
	s_lshr_b32 s12, s12, 29
	s_add_i32 s12, s10, s12
	s_ashr_i32 s13, s12, 3
	s_and_b32 s12, s12, -8
	s_sub_i32 s12, s10, s12
	s_cmp_lt_i32 s12, 0
	s_cselect_b32 s16, s14, 0x160
	s_mul_i32 s12, s12, s16
	s_add_i32 s12, s12, s13
	s_mul_hi_i32 s13, s12, 0x2e8ba2e9
	s_lshr_b32 s16, s13, 31
	s_ashr_i32 s13, s13, 3
	s_add_i32 s13, s13, s16
	s_lshl_b32 s16, s13, 1
	s_sub_i32 s17, 0x80, s16
	s_min_i32 s17, s17, 2
	s_abs_i32 s17, s17
	v_cvt_f32_u32_e32 v7, s17
	s_sub_i32 s20, 0, s17
	s_mul_i32 s13, s13, 44
	s_sub_i32 s12, s12, s13
	v_rcp_iflag_f32_e32 v7, v7
	s_ashr_i32 s13, s12, 31
	s_abs_i32 s12, s12
	v_mul_f32_e32 v7, 0x4f7ffffe, v7
	v_cvt_u32_f32_e32 v7, v7
	s_nop 0
	v_readfirstlane_b32 s21, v7
	s_mul_i32 s20, s20, s21
	s_mul_hi_u32 s20, s21, s20
	s_add_i32 s21, s21, s20
	s_mul_hi_u32 s20, s12, s21
	s_mul_i32 s20, s20, s17
	s_sub_i32 s12, s12, s20
	s_sub_i32 s20, s12, s17
	s_cmp_ge_u32 s12, s17
	s_cselect_b32 s12, s20, s12
	s_sub_i32 s20, s12, s17
	s_cmp_ge_u32 s12, s17
	s_cselect_b32 s12, s20, s12
	s_xor_b32 s12, s12, s13
	s_sub_i32 s12, s12, s13
	s_add_i32 s16, s16, s12
	s_and_saveexec_b64 s[12:13], s[6:7]
	v_lshl_add_u32 v160, s16, 8, v4
	v_ashrrev_i32_e32 v161, 31, v160
	v_lshlrev_b64 v[160:161], 6, v[160:161]
	v_lshl_add_u64 v[24:25], s[8:9], 0, v[160:161]
	global_load_dwordx4 v[160:163], v[24:25], off
	global_load_dwordx4 v[164:167], v[24:25], off offset:16
	global_load_dwordx4 v[168:171], v[24:25], off offset:32
	global_load_dwordx4 v[172:175], v[24:25], off offset:48
	s_or_b64 exec, exec, s[12:13]
	s_add_u32 s10, s10, s46
	s_addc_u32 s11, s11, s47
	s_ashr_i32 s12, s10, 31
	s_lshr_b32 s12, s12, 29
	s_add_i32 s12, s10, s12
	s_ashr_i32 s13, s12, 3
	s_and_b32 s12, s12, -8
	s_sub_i32 s12, s10, s12
	s_cmp_lt_i32 s12, 0
	s_cselect_b32 s16, s14, 0x160
	s_mul_i32 s12, s12, s16
	s_add_i32 s12, s12, s13
	s_mul_hi_i32 s13, s12, 0x2e8ba2e9
	s_lshr_b32 s16, s13, 31
	s_ashr_i32 s13, s13, 3
	s_add_i32 s13, s13, s16
	s_lshl_b32 s16, s13, 1
	s_sub_i32 s17, 0x80, s16
	s_min_i32 s17, s17, 2
	s_abs_i32 s17, s17
	v_cvt_f32_u32_e32 v7, s17
	s_sub_i32 s20, 0, s17
	s_mul_i32 s13, s13, 44
	s_sub_i32 s12, s12, s13
	v_rcp_iflag_f32_e32 v7, v7
	s_ashr_i32 s13, s12, 31
	s_abs_i32 s12, s12
	v_mul_f32_e32 v7, 0x4f7ffffe, v7
	v_cvt_u32_f32_e32 v7, v7
	s_nop 0
	v_readfirstlane_b32 s21, v7
	s_mul_i32 s20, s20, s21
	s_mul_hi_u32 s20, s21, s20
	s_add_i32 s21, s21, s20
	s_mul_hi_u32 s20, s12, s21
	s_mul_i32 s20, s20, s17
	s_sub_i32 s12, s12, s20
	s_sub_i32 s20, s12, s17
	s_cmp_ge_u32 s12, s17
	s_cselect_b32 s12, s20, s12
	s_sub_i32 s20, s12, s17
	s_cmp_ge_u32 s12, s17
	s_cselect_b32 s12, s20, s12
	s_xor_b32 s12, s12, s13
	s_sub_i32 s12, s12, s13
	s_add_i32 s16, s16, s12
	s_and_saveexec_b64 s[12:13], s[6:7]
	v_lshl_add_u32 v176, s16, 8, v4
	v_ashrrev_i32_e32 v177, 31, v176
	v_lshlrev_b64 v[176:177], 6, v[176:177]
	v_lshl_add_u64 v[24:25], s[8:9], 0, v[176:177]
	global_load_dwordx4 v[176:179], v[24:25], off
	global_load_dwordx4 v[180:183], v[24:25], off offset:16
	global_load_dwordx4 v[184:187], v[24:25], off offset:32
	global_load_dwordx4 v[188:191], v[24:25], off offset:48
	s_or_b64 exec, exec, s[12:13]
	s_add_u32 s10, s10, s46
	s_addc_u32 s11, s11, s47
	s_ashr_i32 s12, s10, 31
	s_lshr_b32 s12, s12, 29
	s_add_i32 s12, s10, s12
	s_ashr_i32 s13, s12, 3
	s_and_b32 s12, s12, -8
	s_sub_i32 s12, s10, s12
	s_cmp_lt_i32 s12, 0
	s_cselect_b32 s16, s14, 0x160
	s_mul_i32 s12, s12, s16
	s_add_i32 s12, s12, s13
	s_mul_hi_i32 s13, s12, 0x2e8ba2e9
	s_lshr_b32 s16, s13, 31
	s_ashr_i32 s13, s13, 3
	s_add_i32 s13, s13, s16
	s_lshl_b32 s16, s13, 1
	s_sub_i32 s17, 0x80, s16
	s_min_i32 s17, s17, 2
	s_abs_i32 s17, s17
	v_cvt_f32_u32_e32 v7, s17
	s_sub_i32 s20, 0, s17
	s_mul_i32 s13, s13, 44
	s_sub_i32 s12, s12, s13
	v_rcp_iflag_f32_e32 v7, v7
	s_ashr_i32 s13, s12, 31
	s_abs_i32 s12, s12
	v_mul_f32_e32 v7, 0x4f7ffffe, v7
	v_cvt_u32_f32_e32 v7, v7
	s_nop 0
	v_readfirstlane_b32 s21, v7
	s_mul_i32 s20, s20, s21
	s_mul_hi_u32 s20, s21, s20
	s_add_i32 s21, s21, s20
	s_mul_hi_u32 s20, s12, s21
	s_mul_i32 s20, s20, s17
	s_sub_i32 s12, s12, s20
	s_sub_i32 s20, s12, s17
	s_cmp_ge_u32 s12, s17
	s_cselect_b32 s12, s20, s12
	s_sub_i32 s20, s12, s17
	s_cmp_ge_u32 s12, s17
	s_cselect_b32 s12, s20, s12
	s_xor_b32 s12, s12, s13
	s_sub_i32 s12, s12, s13
	s_add_i32 s16, s16, s12
	s_and_saveexec_b64 s[12:13], s[6:7]
	v_lshl_add_u32 v192, s16, 8, v4
	v_ashrrev_i32_e32 v193, 31, v192
	v_lshlrev_b64 v[192:193], 6, v[192:193]
	v_lshl_add_u64 v[24:25], s[8:9], 0, v[192:193]
	global_load_dwordx4 v[192:195], v[24:25], off
	global_load_dwordx4 v[196:199], v[24:25], off offset:16
	global_load_dwordx4 v[200:203], v[24:25], off offset:32
	global_load_dwordx4 v[204:207], v[24:25], off offset:48
	s_or_b64 exec, exec, s[12:13]
	s_and_saveexec_b64 s[12:13], s[6:7]
	s_waitcnt vmcnt(0)
; __device__ __forceinline__ float row_rstd(const float* ssq, int row) {
;     const f32x4* p = (const f32x4*)(ssq + (size_t)row * 16);
;     const f32x4 a = p[0], b = p[1], c = p[2], d = p[3];
;     const float s = ((a[0] + a[1]) + (a[2] + a[3])) + ((b[0] + b[1]) + (b[2] + b[3])) + ((c[0] + c[1]) + (c[2] + c[3])) + ((d[0] + d[1]) + (d[2] + d[3]));
;     return rsqrtf(s * (1.0f / 1024.0f) + EPS);
; }
; __global__ void __launch_bounds__(512, 2) hybrid_fwd(Args args) {
;     ...
;         { pg8::Unit pu; for (int i = 0; S.next(i, pu); ++i) if (tid < 256) rst[i * 256 + tid] = row_rstd(SSQ + 3 * SSQ_STRIDE, pu.pm * 256 + tid);
	v_mov_b32_e32 v24, v33
	v_mov_b32_e32 v25, v34
	v_mov_b32_e32 v33, v35
	v_mov_b32_e32 v34, v37
	v_mov_b32_e32 v35, v38
	v_mov_b32_e32 v37, v39
	v_pk_add_f32 v[32:33], v[24:25], v[32:33]
	v_pk_add_f32 v[34:35], v[34:35], v[36:37]
	v_pk_add_f32 v[32:33], v[32:33], v[32:33] op_sel:[0,1] op_sel_hi:[1,0]
	v_pk_add_f32 v[34:35], v[34:35], v[34:35] op_sel:[0,1] op_sel_hi:[1,0]
	v_add_f32_e32 v38, v40, v41
	v_add_f32_e32 v40, v42, v43
	v_mov_b32_e32 v39, v46
	v_mov_b32_e32 v41, v47
	v_mov_b32_e32 v33, v44
	v_mov_b32_e32 v35, v45
	v_pk_add_f32 v[36:37], v[38:39], v[40:41]
	v_pk_add_f32 v[32:33], v[32:33], v[34:35]
	s_nop 0
	v_pk_add_f32 v[32:33], v[32:33], v[36:37]
	s_nop 0
	v_add_f32_e32 v7, v32, v33
	v_fmamk_f32 v7, v7, 0x3a800000, v6
	v_mul_f32_e32 v32, 0x4b800000, v7
	v_cmp_gt_f32_e32 vcc, s15, v7
	s_nop 1
	v_cndmask_b32_e32 v7, v7, v32, vcc
	v_rsq_f32_e32 v7, v7
	s_nop 0
	v_mul_f32_e32 v32, 0x45800000, v7
	v_cndmask_b32_e32 v7, v7, v32, vcc
	ds_write_b32 v5, v7
	v_mov_b32_e32 v24, v49
	v_mov_b32_e32 v25, v50
	v_mov_b32_e32 v49, v51
	v_mov_b32_e32 v50, v53
	v_mov_b32_e32 v51, v54
	v_mov_b32_e32 v53, v55
	v_pk_add_f32 v[48:49], v[24:25], v[48:49]
	v_pk_add_f32 v[50:51], v[50:51], v[52:53]
	v_pk_add_f32 v[48:49], v[48:49], v[48:49] op_sel:[0,1] op_sel_hi:[1,0]
	v_pk_add_f32 v[50:51], v[50:51], v[50:51] op_sel:[0,1] op_sel_hi:[1,0]
	v_add_f32_e32 v54, v56, v57
	v_add_f32_e32 v56, v58, v59
	v_mov_b32_e32 v55, v62
	v_mov_b32_e32 v57, v63
	v_mov_b32_e32 v49, v60
	v_mov_b32_e32 v51, v61
	v_pk_add_f32 v[52:53], v[54:55], v[56:57]
	v_pk_add_f32 v[48:49], v[48:49], v[50:51]
	s_nop 0
	v_pk_add_f32 v[48:49], v[48:49], v[52:53]
	s_nop 0
	v_add_f32_e32 v7, v48, v49
	v_fmamk_f32 v7, v7, 0x3a800000, v6
	v_mul_f32_e32 v48, 0x4b800000, v7
	v_cmp_gt_f32_e32 vcc, s15, v7
	s_nop 1
	v_cndmask_b32_e32 v7, v7, v48, vcc
	v_rsq_f32_e32 v7, v7
	s_nop 0
	v_mul_f32_e32 v48, 0x45800000, v7
	v_cndmask_b32_e32 v7, v7, v48, vcc
	ds_write_b32 v5, v7 offset:1024
	v_mov_b32_e32 v24, v65
	v_mov_b32_e32 v25, v66
	v_mov_b32_e32 v65, v67
	v_mov_b32_e32 v66, v69
	v_mov_b32_e32 v67, v70
	v_mov_b32_e32 v69, v71
	v_pk_add_f32 v[64:65], v[24:25], v[64:65]
	v_pk_add_f32 v[66:67], v[66:67], v[68:69]
	v_pk_add_f32 v[64:65], v[64:65], v[64:65] op_sel:[0,1] op_sel_hi:[1,0]
	v_pk_add_f32 v[66:67], v[66:67], v[66:67] op_sel:[0,1] op_sel_hi:[1,0]
	v_add_f32_e32 v70, v72, v73
	v_add_f32_e32 v72, v74, v75
	v_mov_b32_e32 v71, v78
	v_mov_b32_e32 v73, v79
	v_mov_b32_e32 v65, v76
	v_mov_b32_e32 v67, v77
	v_pk_add_f32 v[68:69], v[70:71], v[72:73]
	v_pk_add_f32 v[64:65], v[64:65], v[66:67]
	s_nop 0
	v_pk_add_f32 v[64:65], v[64:65], v[68:69]
	s_nop 0
	v_add_f32_e32 v7, v64, v65
	v_fmamk_f32 v7, v7, 0x3a800000, v6
	v_mul_f32_e32 v64, 0x4b800000, v7
	v_cmp_gt_f32_e32 vcc, s15, v7
	s_nop 1
	v_cndmask_b32_e32 v7, v7, v64, vcc
	v_rsq_f32_e32 v7, v7
	s_nop 0
	v_mul_f32_e32 v64, 0x45800000, v7
	v_cndmask_b32_e32 v7, v7, v64, vcc
	ds_write_b32 v5, v7 offset:2048
	v_mov_b32_e32 v24, v81
	v_mov_b32_e32 v25, v82
	v_mov_b32_e32 v81, v83
	v_mov_b32_e32 v82, v85
	v_mov_b32_e32 v83, v86
	v_mov_b32_e32 v85, v87
	v_pk_add_f32 v[80:81], v[24:25], v[80:81]
	v_pk_add_f32 v[82:83], v[82:83], v[84:85]
	v_pk_add_f32 v[80:81], v[80:81], v[80:81] op_sel:[0,1] op_sel_hi:[1,0]
	v_pk_add_f32 v[82:83], v[82:83], v[82:83] op_sel:[0,1] op_sel_hi:[1,0]
	v_add_f32_e32 v86, v88, v89
	v_add_f32_e32 v88, v90, v91
	v_mov_b32_e32 v87, v94
	v_mov_b32_e32 v89, v95
	v_mov_b32_e32 v81, v92
	v_mov_b32_e32 v83, v93
	v_pk_add_f32 v[84:85], v[86:87], v[88:89]
	v_pk_add_f32 v[80:81], v[80:81], v[82:83]
	s_nop 0
	v_pk_add_f32 v[80:81], v[80:81], v[84:85]
	s_nop 0
	v_add_f32_e32 v7, v80, v81
	v_fmamk_f32 v7, v7, 0x3a800000, v6
	v_mul_f32_e32 v80, 0x4b800000, v7
	v_cmp_gt_f32_e32 vcc, s15, v7
	s_nop 1
	v_cndmask_b32_e32 v7, v7, v80, vcc
	v_rsq_f32_e32 v7, v7
	s_nop 0
	v_mul_f32_e32 v80, 0x45800000, v7
	v_cndmask_b32_e32 v7, v7, v80, vcc
	ds_write_b32 v5, v7 offset:3072
	v_mov_b32_e32 v24, v97
	v_mov_b32_e32 v25, v98
	v_mov_b32_e32 v97, v99
	v_mov_b32_e32 v98, v101
	v_mov_b32_e32 v99, v102
	v_mov_b32_e32 v101, v103
	v_pk_add_f32 v[96:97], v[24:25], v[96:97]
	v_pk_add_f32 v[98:99], v[98:99], v[100:101]
	v_pk_add_f32 v[96:97], v[96:97], v[96:97] op_sel:[0,1] op_sel_hi:[1,0]
	v_pk_add_f32 v[98:99], v[98:99], v[98:99] op_sel:[0,1] op_sel_hi:[1,0]
	v_add_f32_e32 v102, v104, v105
	v_add_f32_e32 v104, v106, v107
	v_mov_b32_e32 v103, v110
	v_mov_b32_e32 v105, v111
	v_mov_b32_e32 v97, v108
	v_mov_b32_e32 v99, v109
	v_pk_add_f32 v[100:101], v[102:103], v[104:105]
	v_pk_add_f32 v[96:97], v[96:97], v[98:99]
	s_nop 0
	v_pk_add_f32 v[96:97], v[96:97], v[100:101]
	s_nop 0
	v_add_f32_e32 v7, v96, v97
	v_fmamk_f32 v7, v7, 0x3a800000, v6
	v_mul_f32_e32 v96, 0x4b800000, v7
	v_cmp_gt_f32_e32 vcc, s15, v7
	s_nop 1
	v_cndmask_b32_e32 v7, v7, v96, vcc
	v_rsq_f32_e32 v7, v7
	s_nop 0
	v_mul_f32_e32 v96, 0x45800000, v7
	v_cndmask_b32_e32 v7, v7, v96, vcc
	ds_write_b32 v5, v7 offset:4096
	v_mov_b32_e32 v24, v113
	v_mov_b32_e32 v25, v114
	v_mov_b32_e32 v113, v115
	v_mov_b32_e32 v114, v117
	v_mov_b32_e32 v115, v118
	v_mov_b32_e32 v117, v119
	v_pk_add_f32 v[112:113], v[24:25], v[112:113]
	v_pk_add_f32 v[114:115], v[114:115], v[116:117]
	v_pk_add_f32 v[112:113], v[112:113], v[112:113] op_sel:[0,1] op_sel_hi:[1,0]
	v_pk_add_f32 v[114:115], v[114:115], v[114:115] op_sel:[0,1] op_sel_hi:[1,0]
	v_add_f32_e32 v118, v120, v121
	v_add_f32_e32 v120, v122, v123
	v_mov_b32_e32 v119, v126
	v_mov_b32_e32 v121, v127
	v_mov_b32_e32 v113, v124
	v_mov_b32_e32 v115, v125
	v_pk_add_f32 v[116:117], v[118:119], v[120:121]
	v_pk_add_f32 v[112:113], v[112:113], v[114:115]
	s_nop 0
; __device__ __forceinline__ float row_rstd(const float* ssq, int row) {
;     const f32x4* p = (const f32x4*)(ssq + (size_t)row * 16);
;     const f32x4 a = p[0], b = p[1], c = p[2], d = p[3];
;     const float s = ((a[0] + a[1]) + (a[2] + a[3])) + ((b[0] + b[1]) + (b[2] + b[3])) + ((c[0] + c[1]) + (c[2] + c[3])) + ((d[0] + d[1]) + (d[2] + d[3]));
;     return rsqrtf(s * (1.0f / 1024.0f) + EPS);
; }
; __global__ void __launch_bounds__(512, 2) hybrid_fwd(Args args) {
;     ...
;         { pg8::Unit pu; for (int i = 0; S.next(i, pu); ++i) if (tid < 256) rst[i * 256 + tid] = row_rstd(SSQ + 3 * SSQ_STRIDE, pu.pm * 256 + tid);
	v_pk_add_f32 v[112:113], v[112:113], v[116:117]
	s_nop 0
	v_add_f32_e32 v7, v112, v113
	v_fmamk_f32 v7, v7, 0x3a800000, v6
	v_mul_f32_e32 v112, 0x4b800000, v7
	v_cmp_gt_f32_e32 vcc, s15, v7
	s_nop 1
	v_cndmask_b32_e32 v7, v7, v112, vcc
	v_rsq_f32_e32 v7, v7
	s_nop 0
	v_mul_f32_e32 v112, 0x45800000, v7
	v_cndmask_b32_e32 v7, v7, v112, vcc
	ds_write_b32 v5, v7 offset:5120
	v_mov_b32_e32 v24, v129
	v_mov_b32_e32 v25, v130
	v_mov_b32_e32 v129, v131
	v_mov_b32_e32 v130, v133
	v_mov_b32_e32 v131, v134
	v_mov_b32_e32 v133, v135
	v_pk_add_f32 v[128:129], v[24:25], v[128:129]
	v_pk_add_f32 v[130:131], v[130:131], v[132:133]
	v_pk_add_f32 v[128:129], v[128:129], v[128:129] op_sel:[0,1] op_sel_hi:[1,0]
	v_pk_add_f32 v[130:131], v[130:131], v[130:131] op_sel:[0,1] op_sel_hi:[1,0]
	v_add_f32_e32 v134, v136, v137
	v_add_f32_e32 v136, v138, v139
	v_mov_b32_e32 v135, v142
	v_mov_b32_e32 v137, v143
	v_mov_b32_e32 v129, v140
	v_mov_b32_e32 v131, v141
	v_pk_add_f32 v[132:133], v[134:135], v[136:137]
	v_pk_add_f32 v[128:129], v[128:129], v[130:131]
	s_nop 0
	v_pk_add_f32 v[128:129], v[128:129], v[132:133]
	s_nop 0
	v_add_f32_e32 v7, v128, v129
	v_fmamk_f32 v7, v7, 0x3a800000, v6
	v_mul_f32_e32 v128, 0x4b800000, v7
	v_cmp_gt_f32_e32 vcc, s15, v7
	s_nop 1
	v_cndmask_b32_e32 v7, v7, v128, vcc
	v_rsq_f32_e32 v7, v7
	s_nop 0
	v_mul_f32_e32 v128, 0x45800000, v7
	v_cndmask_b32_e32 v7, v7, v128, vcc
	ds_write_b32 v5, v7 offset:6144
	v_mov_b32_e32 v24, v145
	v_mov_b32_e32 v25, v146
	v_mov_b32_e32 v145, v147
	v_mov_b32_e32 v146, v149
	v_mov_b32_e32 v147, v150
	v_mov_b32_e32 v149, v151
	v_pk_add_f32 v[144:145], v[24:25], v[144:145]
	v_pk_add_f32 v[146:147], v[146:147], v[148:149]
	v_pk_add_f32 v[144:145], v[144:145], v[144:145] op_sel:[0,1] op_sel_hi:[1,0]
	v_pk_add_f32 v[146:147], v[146:147], v[146:147] op_sel:[0,1] op_sel_hi:[1,0]
	v_add_f32_e32 v150, v152, v153
	v_add_f32_e32 v152, v154, v155
	v_mov_b32_e32 v151, v158
	v_mov_b32_e32 v153, v159
	v_mov_b32_e32 v145, v156
	v_mov_b32_e32 v147, v157
	v_pk_add_f32 v[148:149], v[150:151], v[152:153]
	v_pk_add_f32 v[144:145], v[144:145], v[146:147]
	s_nop 0
	v_pk_add_f32 v[144:145], v[144:145], v[148:149]
	s_nop 0
	v_add_f32_e32 v7, v144, v145
	v_fmamk_f32 v7, v7, 0x3a800000, v6
	v_mul_f32_e32 v144, 0x4b800000, v7
	v_cmp_gt_f32_e32 vcc, s15, v7
	s_nop 1
	v_cndmask_b32_e32 v7, v7, v144, vcc
	v_rsq_f32_e32 v7, v7
	s_nop 0
	v_mul_f32_e32 v144, 0x45800000, v7
	v_cndmask_b32_e32 v7, v7, v144, vcc
	ds_write_b32 v5, v7 offset:7168
	v_mov_b32_e32 v24, v161
	v_mov_b32_e32 v25, v162
	v_mov_b32_e32 v161, v163
	v_mov_b32_e32 v162, v165
	v_mov_b32_e32 v163, v166
	v_mov_b32_e32 v165, v167
	v_pk_add_f32 v[160:161], v[24:25], v[160:161]
	v_pk_add_f32 v[162:163], v[162:163], v[164:165]
	v_pk_add_f32 v[160:161], v[160:161], v[160:161] op_sel:[0,1] op_sel_hi:[1,0]
	v_pk_add_f32 v[162:163], v[162:163], v[162:163] op_sel:[0,1] op_sel_hi:[1,0]
	v_add_f32_e32 v166, v168, v169
	v_add_f32_e32 v168, v170, v171
	v_mov_b32_e32 v167, v174
	v_mov_b32_e32 v169, v175
	v_mov_b32_e32 v161, v172
	v_mov_b32_e32 v163, v173
	v_pk_add_f32 v[164:165], v[166:167], v[168:169]
	v_pk_add_f32 v[160:161], v[160:161], v[162:163]
	s_nop 0
	v_pk_add_f32 v[160:161], v[160:161], v[164:165]
	s_nop 0
	v_add_f32_e32 v7, v160, v161
	v_fmamk_f32 v7, v7, 0x3a800000, v6
	v_mul_f32_e32 v160, 0x4b800000, v7
	v_cmp_gt_f32_e32 vcc, s15, v7
	s_nop 1
	v_cndmask_b32_e32 v7, v7, v160, vcc
	v_rsq_f32_e32 v7, v7
	s_nop 0
	v_mul_f32_e32 v160, 0x45800000, v7
	v_cndmask_b32_e32 v7, v7, v160, vcc
	ds_write_b32 v5, v7 offset:8192
	v_mov_b32_e32 v24, v177
	v_mov_b32_e32 v25, v178
	v_mov_b32_e32 v177, v179
	v_mov_b32_e32 v178, v181
	v_mov_b32_e32 v179, v182
	v_mov_b32_e32 v181, v183
	v_pk_add_f32 v[176:177], v[24:25], v[176:177]
	v_pk_add_f32 v[178:179], v[178:179], v[180:181]
	v_pk_add_f32 v[176:177], v[176:177], v[176:177] op_sel:[0,1] op_sel_hi:[1,0]
	v_pk_add_f32 v[178:179], v[178:179], v[178:179] op_sel:[0,1] op_sel_hi:[1,0]
	v_add_f32_e32 v182, v184, v185
	v_add_f32_e32 v184, v186, v187
	v_mov_b32_e32 v183, v190
	v_mov_b32_e32 v185, v191
	v_mov_b32_e32 v177, v188
	v_mov_b32_e32 v179, v189
	v_pk_add_f32 v[180:181], v[182:183], v[184:185]
	v_pk_add_f32 v[176:177], v[176:177], v[178:179]
	s_nop 0
	v_pk_add_f32 v[176:177], v[176:177], v[180:181]
	s_nop 0
	v_add_f32_e32 v7, v176, v177
	v_fmamk_f32 v7, v7, 0x3a800000, v6
	v_mul_f32_e32 v176, 0x4b800000, v7
	v_cmp_gt_f32_e32 vcc, s15, v7
	s_nop 1
	v_cndmask_b32_e32 v7, v7, v176, vcc
	v_rsq_f32_e32 v7, v7
	s_nop 0
	v_mul_f32_e32 v176, 0x45800000, v7
	v_cndmask_b32_e32 v7, v7, v176, vcc
	ds_write_b32 v5, v7 offset:9216
	v_mov_b32_e32 v24, v193
	v_mov_b32_e32 v25, v194
	v_mov_b32_e32 v193, v195
	v_mov_b32_e32 v194, v197
	v_mov_b32_e32 v195, v198
	v_mov_b32_e32 v197, v199
	v_pk_add_f32 v[192:193], v[24:25], v[192:193]
	v_pk_add_f32 v[194:195], v[194:195], v[196:197]
	v_pk_add_f32 v[192:193], v[192:193], v[192:193] op_sel:[0,1] op_sel_hi:[1,0]
	v_pk_add_f32 v[194:195], v[194:195], v[194:195] op_sel:[0,1] op_sel_hi:[1,0]
	v_add_f32_e32 v198, v200, v201
	v_add_f32_e32 v200, v202, v203
	v_mov_b32_e32 v199, v206
	v_mov_b32_e32 v201, v207
	v_mov_b32_e32 v193, v204
	v_mov_b32_e32 v195, v205
	v_pk_add_f32 v[196:197], v[198:199], v[200:201]
	v_pk_add_f32 v[192:193], v[192:193], v[194:195]
	s_nop 0
	v_pk_add_f32 v[192:193], v[192:193], v[196:197]
	s_nop 0
	v_add_f32_e32 v7, v192, v193
	v_fmamk_f32 v7, v7, 0x3a800000, v6
	v_mul_f32_e32 v192, 0x4b800000, v7
	v_cmp_gt_f32_e32 vcc, s15, v7
	s_nop 1
	v_cndmask_b32_e32 v7, v7, v192, vcc
	v_rsq_f32_e32 v7, v7
	s_nop 0
	v_mul_f32_e32 v192, 0x45800000, v7
	v_cndmask_b32_e32 v7, v7, v192, vcc
	ds_write_b32 v5, v7 offset:10240
	s_or_b64 exec, exec, s[12:13]
	s_branch .LBB0_1267
